# EpiResid epilogue (FFN1-out, out-proj): 8-byte fp16 store pairs merged via v_permlane16_swap into 16-byte sc1 stores; counted vmcnt adjusted
# speedup vs baseline: 1.0106x; 1.0106x over previous
.LBB0_801:
	s_mov_b32 s15, s93
	s_mov_b32 s18, s33
	v_mov_b32_e32 v138, s15
	ds_read2_b32 v[138:139], v138 offset1:1
	s_mov_b32 s15, s92
	s_ashr_i32 s15, s14, 31
	s_lshl_b64 s[14:15], s[14:15], 8
	s_waitcnt lgkmcnt(0)
	v_readfirstlane_b32 s16, v138
	v_lshl_or_b32 v138, s43, 8, v155
	v_lshl_add_u64 v[140:141], s[14:15], 0, v[132:133]
	v_readfirstlane_b32 s17, v139
	v_ashrrev_i32_e32 v139, 31, v138
	v_lshlrev_b64 v[144:145], 11, v[140:141]
	v_lshl_add_u64 v[142:143], s[16:17], 0, v[144:145]
	v_lshlrev_b64 v[146:147], 1, v[138:139]
	s_mov_b32 s18, s33
	v_lshl_add_u64 v[158:159], v[142:143], 0, v[146:147]
	global_load_dwordx2 v[160:161], v[158:159], off
	global_load_dwordx2 v[162:163], v[158:159], off offset:32
	global_load_dwordx2 v[164:165], v[158:159], off offset:256
	global_load_dwordx2 v[166:167], v[158:159], off offset:288
	v_mov_b32_e32 v142, s18
	ds_read2_b32 v[148:149], v142 offset1:1
	v_lshl_add_u64 v[142:143], s[16:17], 0, v[146:147]
	v_lshl_add_u64 v[144:145], v[142:143], 0, v[144:145]
	v_add_co_u32_e32 v146, vcc, s50, v144
	s_waitcnt lgkmcnt(0)
	v_readfirstlane_b32 s18, v148
	v_addc_co_u32_e32 v147, vcc, 0, v145, vcc
	v_readfirstlane_b32 s19, v149
	global_load_dwordx2 v[152:153], v[146:147], off
	global_load_dwordx2 v[150:151], v[146:147], off offset:32
	global_load_dwordx2 v[148:149], v[146:147], off offset:256
	s_nop 0
	global_load_dwordx2 v[146:147], v[146:147], off offset:288
	s_lshl_b32 s14, s43, 2
	s_ashr_i32 s15, s14, 31
	s_lshl_b64 s[14:15], s[14:15], 2
	s_add_u32 s14, s18, s14
	s_addc_u32 s15, s19, s15
	s_add_u32 s14, s14, s40
	s_addc_u32 s15, s15, 0
	s_add_u32 s14, s14, 0x10380000
	s_addc_u32 s15, s15, 0
	s_waitcnt vmcnt(0)
	v_cvt_f32_f16_e32 v168, v160
	v_cvt_f32_f16_sdwa v169, v160 dst_sel:DWORD dst_unused:UNUSED_PAD src0_sel:WORD_1
	v_cvt_f32_f16_e32 v160, v161
	v_cvt_f32_f16_sdwa v161, v161 dst_sel:DWORD dst_unused:UNUSED_PAD src0_sel:WORD_1
	v_cvt_f32_f16_e32 v170, v162
	v_cvt_f32_f16_sdwa v171, v162 dst_sel:DWORD dst_unused:UNUSED_PAD src0_sel:WORD_1
	v_cvt_f32_f16_e32 v162, v163
	v_cvt_f32_f16_sdwa v163, v163 dst_sel:DWORD dst_unused:UNUSED_PAD src0_sel:WORD_1
	v_cvt_f32_f16_e32 v172, v164
	v_cvt_f32_f16_sdwa v173, v164 dst_sel:DWORD dst_unused:UNUSED_PAD src0_sel:WORD_1
	v_cvt_f32_f16_e32 v164, v165
	v_cvt_f32_f16_sdwa v165, v165 dst_sel:DWORD dst_unused:UNUSED_PAD src0_sel:WORD_1
	v_cvt_f32_f16_e32 v174, v166
	v_cvt_f32_f16_sdwa v175, v166 dst_sel:DWORD dst_unused:UNUSED_PAD src0_sel:WORD_1
	v_cvt_f32_f16_e32 v166, v167
	v_cvt_f32_f16_sdwa v167, v167 dst_sel:DWORD dst_unused:UNUSED_PAD src0_sel:WORD_1
	v_pk_fma_f32 v[128:129], v[128:129], 0.5, v[160:161] op_sel_hi:[1,0,1]
	v_pk_fma_f32 v[126:127], v[126:127], 0.5, v[168:169] op_sel_hi:[1,0,1]
	v_pk_fma_f32 v[122:123], v[122:123], 0.5, v[170:171] op_sel_hi:[1,0,1]
	v_pk_fma_f32 v[124:125], v[124:125], 0.5, v[162:163] op_sel_hi:[1,0,1]
	v_pk_fma_f32 v[120:121], v[120:121], 0.5, v[164:165] op_sel_hi:[1,0,1]
	v_pk_fma_f32 v[118:119], v[118:119], 0.5, v[172:173] op_sel_hi:[1,0,1]
	v_cvt_f16_f32_e32 v157, v126
	v_cvt_f16_f32_sdwa v160, v127 dst_sel:WORD_1 dst_unused:UNUSED_PAD src0_sel:DWORD
	v_cvt_f16_f32_e32 v161, v128
	v_cvt_f16_f32_sdwa v162, v129 dst_sel:WORD_1 dst_unused:UNUSED_PAD src0_sel:DWORD
	v_cvt_f16_f32_e32 v163, v122
	v_cvt_f16_f32_sdwa v164, v123 dst_sel:WORD_1 dst_unused:UNUSED_PAD src0_sel:DWORD
	v_pk_fma_f32 v[116:117], v[116:117], 0.5, v[166:167] op_sel_hi:[1,0,1]
	v_mul_f32_e32 v127, v127, v127
	v_mul_f32_e32 v129, v129, v129
	v_cvt_f16_f32_e32 v165, v124
	v_cvt_f16_f32_sdwa v166, v125 dst_sel:WORD_1 dst_unused:UNUSED_PAD src0_sel:DWORD
	v_mul_f32_e32 v123, v123, v123
	v_mul_f32_e32 v125, v125, v125
	v_cvt_f16_f32_e32 v167, v118
	v_cvt_f16_f32_sdwa v168, v119 dst_sel:WORD_1 dst_unused:UNUSED_PAD src0_sel:DWORD
	v_cvt_f16_f32_e32 v169, v120
	v_cvt_f16_f32_sdwa v170, v121 dst_sel:WORD_1 dst_unused:UNUSED_PAD src0_sel:DWORD
	v_mul_f32_e32 v171, v119, v119
	v_fmac_f32_e32 v127, v126, v126
	v_fmac_f32_e32 v129, v128, v128
	v_fmac_f32_e32 v123, v122, v122
	v_fmac_f32_e32 v125, v124, v124
	v_mul_f32_e32 v172, v121, v121
	v_fmac_f32_e32 v171, v118, v118
	v_add_f32_e32 v118, v127, v129
	v_add_f32_e32 v119, v123, v125
	v_pk_fma_f32 v[114:115], v[114:115], 0.5, v[174:175] op_sel_hi:[1,0,1]
	v_fmac_f32_e32 v172, v120, v120
	v_add_f32_e32 v124, v118, v119
	v_or_b32_e32 v118, v160, v157
	v_or_b32_e32 v119, v162, v161
	v_or_b32_e32 v120, v164, v163
	v_cvt_f16_f32_e32 v173, v114
	v_cvt_f16_f32_sdwa v174, v115 dst_sel:WORD_1 dst_unused:UNUSED_PAD src0_sel:DWORD
	v_or_b32_e32 v121, v166, v165
	v_or_b32_e32 v122, v168, v167
	v_or_b32_e32 v123, v170, v169
	v_mov_b32_e32 v240, v118
	v_mov_b32_e32 v241, v119
	v_mov_b32_e32 v242, v120
	v_mov_b32_e32 v243, v121
	v_mbcnt_lo_u32_b32 v222, -1, 0
	v_mbcnt_hi_u32_b32 v222, -1, v222
	v_bfe_u32 v222, v222, 4, 1
	v_mul_u32_u24_e32 v222, 24, v222
	v_mov_b32_e32 v223, 0
	v_permlane16_swap_b32_e32 v240, v242
	v_permlane16_swap_b32_e32 v241, v243
	v_lshl_add_u64 v[222:223], v[158:159], 0, v[222:223]
	global_store_dwordx4 v[222:223], v[240:243], off sc1
	v_mov_b32_e32 v244, v122
	v_mov_b32_e32 v245, v123
	v_cvt_f16_f32_e32 v119, v116
	v_cvt_f16_f32_sdwa v120, v117 dst_sel:WORD_1 dst_unused:UNUSED_PAD src0_sel:DWORD
	v_mul_f32_e32 v115, v115, v115
	v_fmac_f32_e32 v115, v114, v114
	v_mul_f32_e32 v114, v117, v117
	v_add_f32_e32 v118, v171, v172
	v_fmac_f32_e32 v114, v116, v116
	v_add_f32_e32 v121, v124, v118
	v_or_b32_e32 v118, v174, v173
	v_or_b32_e32 v119, v120, v119
	v_add_f32_e32 v114, v115, v114
	v_mov_b32_e32 v246, v118
	v_mov_b32_e32 v247, v119
	v_mbcnt_lo_u32_b32 v222, -1, 0
	v_mbcnt_hi_u32_b32 v222, -1, v222
	v_bfe_u32 v222, v222, 4, 1
	v_mul_u32_u24_e32 v222, 24, v222
	v_mov_b32_e32 v223, 0
	v_permlane16_swap_b32_e32 v244, v246
	v_permlane16_swap_b32_e32 v245, v247
	v_lshl_add_u64 v[222:223], v[158:159], 0, v[222:223]
	global_store_dwordx4 v[222:223], v[244:247], off offset:256 sc1
	v_add_f32_e32 v114, v121, v114
	v_mov_b32_e32 v115, v114
	s_nop 1
	v_permlane16_swap_b32_e32 v115, v114
	s_waitcnt lgkmcnt(0)
	v_add_f32_e32 v114, v114, v115
	v_mov_b32_e32 v115, v1
	s_nop 0
	v_mbcnt_lo_u32_b32 v115, -1, v115
	v_mbcnt_hi_u32_b32 v115, -1, v115
	v_lshlrev_b32_e32 v115, 2, v115
	v_xor_b32_e32 v115, 0x80, v115
	ds_bpermute_b32 v115, v115, v114
	s_and_saveexec_b64 s[18:19], s[0:1]
	s_cbranch_execz .LBB0_803
	v_lshlrev_b64 v[116:117], 6, v[140:141]
	v_lshl_add_u64 v[116:117], s[14:15], 0, v[116:117]
	s_waitcnt lgkmcnt(0)
	v_add_f32_e32 v114, v114, v115
	global_store_dword v[116:117], v114, off
.LBB0_803:
	s_or_b64 exec, exec, s[18:19]
	v_cvt_f32_f16_sdwa v117, v152 dst_sel:DWORD dst_unused:UNUSED_PAD src0_sel:WORD_1
	v_cvt_f32_f16_e32 v116, v152
	v_cvt_f32_f16_sdwa v119, v153 dst_sel:DWORD dst_unused:UNUSED_PAD src0_sel:WORD_1
	v_cvt_f32_f16_e32 v118, v153
	s_mov_b32 s18, 0x10000
	v_cvt_f32_f16_sdwa v129, v146 dst_sel:DWORD dst_unused:UNUSED_PAD src0_sel:WORD_1
	v_cvt_f32_f16_e32 v128, v146
	v_add_co_u32_e32 v146, vcc, s18, v144
	v_cvt_f32_f16_sdwa v125, v148 dst_sel:DWORD dst_unused:UNUSED_PAD src0_sel:WORD_1
	v_cvt_f32_f16_e32 v124, v148
	v_cvt_f32_f16_sdwa v127, v149 dst_sel:DWORD dst_unused:UNUSED_PAD src0_sel:WORD_1
	v_cvt_f32_f16_e32 v126, v149
	v_cvt_f32_f16_sdwa v149, v147 dst_sel:DWORD dst_unused:UNUSED_PAD src0_sel:WORD_1
	v_cvt_f32_f16_e32 v148, v147
	v_addc_co_u32_e32 v147, vcc, 0, v145, vcc
	v_cvt_f32_f16_sdwa v121, v150 dst_sel:DWORD dst_unused:UNUSED_PAD src0_sel:WORD_1
	v_cvt_f32_f16_e32 v120, v150
	v_cvt_f32_f16_sdwa v123, v151 dst_sel:DWORD dst_unused:UNUSED_PAD src0_sel:WORD_1
	v_cvt_f32_f16_e32 v122, v151
	v_pk_fma_f32 v[150:151], v[112:113], 0.5, v[118:119] op_sel_hi:[1,0,1]
	v_pk_fma_f32 v[152:153], v[110:111], 0.5, v[116:117] op_sel_hi:[1,0,1]
	global_load_dwordx2 v[118:119], v[146:147], off
	global_load_dwordx2 v[116:117], v[146:147], off offset:32
	global_load_dwordx2 v[112:113], v[146:147], off offset:256
	global_load_dwordx2 v[110:111], v[146:147], off offset:288
	v_cvt_f16_f32_e32 v157, v152
	v_cvt_f16_f32_sdwa v158, v153 dst_sel:WORD_1 dst_unused:UNUSED_PAD src0_sel:DWORD
	v_cvt_f16_f32_e32 v159, v150
	v_cvt_f16_f32_sdwa v160, v151 dst_sel:WORD_1 dst_unused:UNUSED_PAD src0_sel:DWORD
	v_pk_fma_f32 v[108:109], v[108:109], 0.5, v[122:123] op_sel_hi:[1,0,1]
	v_pk_fma_f32 v[106:107], v[106:107], 0.5, v[120:121] op_sel_hi:[1,0,1]
	v_cvt_f16_f32_e32 v122, v108
	v_cvt_f16_f32_e32 v120, v106
	v_cvt_f16_f32_sdwa v121, v107 dst_sel:WORD_1 dst_unused:UNUSED_PAD src0_sel:DWORD
	v_cvt_f16_f32_sdwa v123, v109 dst_sel:WORD_1 dst_unused:UNUSED_PAD src0_sel:DWORD
	v_or_b32_e32 v114, 16, v140
	s_waitcnt lgkmcnt(0)
	v_mov_b32_e32 v115, v141
	v_or_b32_e32 v146, v158, v157
	v_or_b32_e32 v147, v160, v159
	v_lshlrev_b64 v[158:159], 11, v[114:115]
	v_lshl_add_u64 v[158:159], s[16:17], 0, v[158:159]
	v_mul_f32_e32 v107, v107, v107
	v_lshl_add_u64 v[158:159], v[138:139], 1, v[158:159]
	v_or_b32_e32 v120, v121, v120
	v_or_b32_e32 v121, v123, v122
	v_fmac_f32_e32 v107, v106, v106
	v_mul_f32_e32 v106, v109, v109
	v_pk_fma_f32 v[104:105], v[104:105], 0.5, v[126:127] op_sel_hi:[1,0,1]
	v_pk_fma_f32 v[102:103], v[102:103], 0.5, v[124:125] op_sel_hi:[1,0,1]
	v_mov_b32_e32 v242, v120
	v_mov_b32_e32 v243, v121
	v_fmac_f32_e32 v106, v108, v108
	v_cvt_f16_f32_e32 v108, v102
	v_cvt_f16_f32_sdwa v109, v103 dst_sel:WORD_1 dst_unused:UNUSED_PAD src0_sel:DWORD
	v_cvt_f16_f32_e32 v120, v104
	v_cvt_f16_f32_sdwa v121, v105 dst_sel:WORD_1 dst_unused:UNUSED_PAD src0_sel:DWORD
	v_mov_b32_e32 v240, v146
	v_mov_b32_e32 v241, v147
	v_mbcnt_lo_u32_b32 v222, -1, 0
	v_mbcnt_hi_u32_b32 v222, -1, v222
	v_bfe_u32 v222, v222, 4, 1
	v_mul_u32_u24_e32 v222, 24, v222
	v_mov_b32_e32 v223, 0
	v_permlane16_swap_b32_e32 v240, v242
	v_permlane16_swap_b32_e32 v241, v243
	v_lshl_add_u64 v[222:223], v[158:159], 0, v[222:223]
	global_store_dwordx4 v[222:223], v[240:243], off sc1
	v_mul_f32_e32 v146, v153, v153
	v_mul_f32_e32 v147, v151, v151
	v_fmac_f32_e32 v146, v152, v152
	v_fmac_f32_e32 v147, v150, v150
	v_add_f32_e32 v146, v146, v147
	v_add_f32_e32 v106, v107, v106
	v_mul_f32_e32 v103, v103, v103
	v_add_f32_e32 v122, v146, v106
	v_or_b32_e32 v106, v109, v108
	v_or_b32_e32 v107, v121, v120
	v_fmac_f32_e32 v103, v102, v102
	v_mul_f32_e32 v102, v105, v105
	v_pk_fma_f32 v[100:101], v[100:101], 0.5, v[148:149] op_sel_hi:[1,0,1]
	v_pk_fma_f32 v[98:99], v[98:99], 0.5, v[128:129] op_sel_hi:[1,0,1]
	v_mov_b32_e32 v244, v106
	v_mov_b32_e32 v245, v107
	v_fmac_f32_e32 v102, v104, v104
	v_cvt_f16_f32_e32 v104, v98
	v_cvt_f16_f32_sdwa v105, v99 dst_sel:WORD_1 dst_unused:UNUSED_PAD src0_sel:DWORD
	v_cvt_f16_f32_e32 v106, v100
	v_cvt_f16_f32_sdwa v107, v101 dst_sel:WORD_1 dst_unused:UNUSED_PAD src0_sel:DWORD
	v_mul_f32_e32 v99, v99, v99
	v_fmac_f32_e32 v99, v98, v98
	v_mul_f32_e32 v98, v101, v101
	v_add_f32_e32 v102, v103, v102
	v_fmac_f32_e32 v98, v100, v100
	v_add_f32_e32 v108, v122, v102
	v_or_b32_e32 v102, v105, v104
	v_or_b32_e32 v103, v107, v106
	v_add_f32_e32 v98, v99, v98
	v_mov_b32_e32 v246, v102
	v_mov_b32_e32 v247, v103
	v_mbcnt_lo_u32_b32 v222, -1, 0
	v_mbcnt_hi_u32_b32 v222, -1, v222
	v_bfe_u32 v222, v222, 4, 1
	v_mul_u32_u24_e32 v222, 24, v222
	v_mov_b32_e32 v223, 0
	v_permlane16_swap_b32_e32 v244, v246
	v_permlane16_swap_b32_e32 v245, v247
	v_lshl_add_u64 v[222:223], v[158:159], 0, v[222:223]
	global_store_dwordx4 v[222:223], v[244:247], off offset:256 sc1
	v_add_f32_e32 v98, v108, v98
	v_mov_b32_e32 v99, v98
	s_nop 1
	v_permlane16_swap_b32_e32 v99, v98
	s_waitcnt lgkmcnt(0)
	v_add_f32_e32 v98, v98, v99
	v_mov_b32_e32 v99, v1
	s_nop 0
	v_mbcnt_lo_u32_b32 v99, -1, v99
	v_mbcnt_hi_u32_b32 v99, -1, v99
	v_lshlrev_b32_e32 v99, 2, v99
	v_xor_b32_e32 v99, 0x80, v99
	ds_bpermute_b32 v99, v99, v98
	s_and_saveexec_b64 s[18:19], s[0:1]
	s_cbranch_execz .LBB0_805
	v_lshlrev_b64 v[100:101], 6, v[114:115]
	v_lshl_add_u64 v[100:101], s[14:15], 0, v[100:101]
	s_waitcnt lgkmcnt(0)
	v_add_f32_e32 v98, v98, v99
	global_store_dword v[100:101], v98, off
.LBB0_805:
	s_or_b64 exec, exec, s[18:19]
	s_waitcnt vmcnt(5)
	v_cvt_f32_f16_sdwa v101, v118 dst_sel:DWORD dst_unused:UNUSED_PAD src0_sel:WORD_1
	v_cvt_f32_f16_e32 v100, v118
	v_cvt_f32_f16_sdwa v103, v119 dst_sel:DWORD dst_unused:UNUSED_PAD src0_sel:WORD_1
	v_cvt_f32_f16_e32 v102, v119
	s_mov_b32 s18, 0x18000
	s_waitcnt vmcnt(3)
	v_cvt_f32_f16_sdwa v109, v112 dst_sel:DWORD dst_unused:UNUSED_PAD src0_sel:WORD_1
	v_cvt_f32_f16_e32 v108, v112
	v_cvt_f32_f16_sdwa v115, v113 dst_sel:DWORD dst_unused:UNUSED_PAD src0_sel:WORD_1
	v_cvt_f32_f16_e32 v114, v113
	s_waitcnt vmcnt(2)
	v_cvt_f32_f16_sdwa v113, v110 dst_sel:DWORD dst_unused:UNUSED_PAD src0_sel:WORD_1
	v_cvt_f32_f16_e32 v112, v110
	v_add_co_u32_e32 v110, vcc, s18, v144
	v_cvt_f32_f16_sdwa v105, v116 dst_sel:DWORD dst_unused:UNUSED_PAD src0_sel:WORD_1
	v_cvt_f32_f16_e32 v104, v116
	v_cvt_f32_f16_sdwa v107, v117 dst_sel:DWORD dst_unused:UNUSED_PAD src0_sel:WORD_1
	v_cvt_f32_f16_e32 v106, v117
	v_cvt_f32_f16_sdwa v117, v111 dst_sel:DWORD dst_unused:UNUSED_PAD src0_sel:WORD_1
	v_cvt_f32_f16_e32 v116, v111
	v_addc_co_u32_e32 v111, vcc, 0, v145, vcc
	v_pk_fma_f32 v[118:119], v[96:97], 0.5, v[102:103] op_sel_hi:[1,0,1]
	v_pk_fma_f32 v[120:121], v[94:95], 0.5, v[100:101] op_sel_hi:[1,0,1]
	global_load_dwordx2 v[102:103], v[110:111], off
	global_load_dwordx2 v[100:101], v[110:111], off offset:32
	global_load_dwordx2 v[96:97], v[110:111], off offset:256
	global_load_dwordx2 v[94:95], v[110:111], off offset:288
	v_cvt_f16_f32_e32 v122, v120
	v_cvt_f16_f32_sdwa v123, v121 dst_sel:WORD_1 dst_unused:UNUSED_PAD src0_sel:DWORD
	v_pk_fma_f32 v[92:93], v[92:93], 0.5, v[106:107] op_sel_hi:[1,0,1]
	v_pk_fma_f32 v[90:91], v[90:91], 0.5, v[104:105] op_sel_hi:[1,0,1]
	v_cvt_f16_f32_e32 v106, v92
	v_cvt_f16_f32_e32 v104, v90
	v_cvt_f16_f32_sdwa v105, v91 dst_sel:WORD_1 dst_unused:UNUSED_PAD src0_sel:DWORD
	v_cvt_f16_f32_sdwa v107, v93 dst_sel:WORD_1 dst_unused:UNUSED_PAD src0_sel:DWORD
	v_or_b32_e32 v98, 32, v140
	s_waitcnt lgkmcnt(0)
	v_mov_b32_e32 v99, v141
	v_cvt_f16_f32_e32 v124, v118
	v_cvt_f16_f32_sdwa v125, v119 dst_sel:WORD_1 dst_unused:UNUSED_PAD src0_sel:DWORD
	v_or_b32_e32 v110, v123, v122
	v_lshlrev_b64 v[122:123], 11, v[98:99]
	v_lshl_add_u64 v[122:123], s[16:17], 0, v[122:123]
	v_mul_f32_e32 v91, v91, v91
	v_lshl_add_u64 v[122:123], v[138:139], 1, v[122:123]
	v_or_b32_e32 v104, v105, v104
	v_or_b32_e32 v105, v107, v106
	v_fmac_f32_e32 v91, v90, v90
	v_mul_f32_e32 v90, v93, v93
	v_pk_fma_f32 v[88:89], v[88:89], 0.5, v[114:115] op_sel_hi:[1,0,1]
	v_pk_fma_f32 v[86:87], v[86:87], 0.5, v[108:109] op_sel_hi:[1,0,1]
	v_or_b32_e32 v111, v125, v124
	v_mov_b32_e32 v242, v104
	v_mov_b32_e32 v243, v105
	v_fmac_f32_e32 v90, v92, v92
	v_cvt_f16_f32_e32 v92, v86
	v_cvt_f16_f32_sdwa v93, v87 dst_sel:WORD_1 dst_unused:UNUSED_PAD src0_sel:DWORD
	v_cvt_f16_f32_e32 v104, v88
	v_cvt_f16_f32_sdwa v105, v89 dst_sel:WORD_1 dst_unused:UNUSED_PAD src0_sel:DWORD
	v_mov_b32_e32 v240, v110
	v_mov_b32_e32 v241, v111
	v_mbcnt_lo_u32_b32 v222, -1, 0
	v_mbcnt_hi_u32_b32 v222, -1, v222
	v_bfe_u32 v222, v222, 4, 1
	v_mul_u32_u24_e32 v222, 24, v222
	v_mov_b32_e32 v223, 0
	v_permlane16_swap_b32_e32 v240, v242
	v_permlane16_swap_b32_e32 v241, v243
	v_lshl_add_u64 v[222:223], v[122:123], 0, v[222:223]
	global_store_dwordx4 v[222:223], v[240:243], off sc1
	v_mul_f32_e32 v110, v121, v121
	v_mul_f32_e32 v111, v119, v119
	v_fmac_f32_e32 v110, v120, v120
	v_fmac_f32_e32 v111, v118, v118
	v_add_f32_e32 v110, v110, v111
	v_add_f32_e32 v90, v91, v90
	v_mul_f32_e32 v87, v87, v87
	v_add_f32_e32 v106, v110, v90
	v_or_b32_e32 v90, v93, v92
	v_or_b32_e32 v91, v105, v104
	v_fmac_f32_e32 v87, v86, v86
	v_mul_f32_e32 v86, v89, v89
	v_pk_fma_f32 v[84:85], v[84:85], 0.5, v[116:117] op_sel_hi:[1,0,1]
	v_pk_fma_f32 v[82:83], v[82:83], 0.5, v[112:113] op_sel_hi:[1,0,1]
	v_mov_b32_e32 v244, v90
	v_mov_b32_e32 v245, v91
	v_fmac_f32_e32 v86, v88, v88
	v_cvt_f16_f32_e32 v88, v82
	v_cvt_f16_f32_sdwa v89, v83 dst_sel:WORD_1 dst_unused:UNUSED_PAD src0_sel:DWORD
	v_cvt_f16_f32_e32 v90, v84
	v_cvt_f16_f32_sdwa v91, v85 dst_sel:WORD_1 dst_unused:UNUSED_PAD src0_sel:DWORD
	v_mul_f32_e32 v83, v83, v83
	v_fmac_f32_e32 v83, v82, v82
	v_mul_f32_e32 v82, v85, v85
	v_add_f32_e32 v86, v87, v86
	v_fmac_f32_e32 v82, v84, v84
	v_add_f32_e32 v92, v106, v86
	v_or_b32_e32 v86, v89, v88
	v_or_b32_e32 v87, v91, v90
	v_add_f32_e32 v82, v83, v82
	v_mov_b32_e32 v246, v86
	v_mov_b32_e32 v247, v87
	v_mbcnt_lo_u32_b32 v222, -1, 0
	v_mbcnt_hi_u32_b32 v222, -1, v222
	v_bfe_u32 v222, v222, 4, 1
	v_mul_u32_u24_e32 v222, 24, v222
	v_mov_b32_e32 v223, 0
	v_permlane16_swap_b32_e32 v244, v246
	v_permlane16_swap_b32_e32 v245, v247
	v_lshl_add_u64 v[222:223], v[122:123], 0, v[222:223]
	global_store_dwordx4 v[222:223], v[244:247], off offset:256 sc1
	v_add_f32_e32 v82, v92, v82
	v_mov_b32_e32 v83, v82
	s_nop 1
	v_permlane16_swap_b32_e32 v83, v82
	s_waitcnt lgkmcnt(0)
	v_add_f32_e32 v82, v82, v83
	v_mov_b32_e32 v83, v1
	s_nop 0
	v_mbcnt_lo_u32_b32 v83, -1, v83
	v_mbcnt_hi_u32_b32 v83, -1, v83
	v_lshlrev_b32_e32 v83, 2, v83
	v_xor_b32_e32 v83, 0x80, v83
	ds_bpermute_b32 v83, v83, v82
	s_and_saveexec_b64 s[18:19], s[0:1]
	s_cbranch_execz .LBB0_807
	v_lshlrev_b64 v[84:85], 6, v[98:99]
	v_lshl_add_u64 v[84:85], s[14:15], 0, v[84:85]
	s_waitcnt lgkmcnt(0)
	v_add_f32_e32 v82, v82, v83
	global_store_dword v[84:85], v82, off
.LBB0_807:
	s_or_b64 exec, exec, s[18:19]
	s_waitcnt vmcnt(5)
	v_cvt_f32_f16_sdwa v85, v102 dst_sel:DWORD dst_unused:UNUSED_PAD src0_sel:WORD_1
	v_cvt_f32_f16_e32 v84, v102
	v_cvt_f32_f16_sdwa v87, v103 dst_sel:DWORD dst_unused:UNUSED_PAD src0_sel:WORD_1
	v_cvt_f32_f16_e32 v86, v103
	s_mov_b32 s18, 0x40000
	s_waitcnt vmcnt(3)
	v_cvt_f32_f16_sdwa v93, v96 dst_sel:DWORD dst_unused:UNUSED_PAD src0_sel:WORD_1
	v_cvt_f32_f16_e32 v92, v96
	v_cvt_f32_f16_sdwa v99, v97 dst_sel:DWORD dst_unused:UNUSED_PAD src0_sel:WORD_1
	v_cvt_f32_f16_e32 v98, v97
	s_waitcnt vmcnt(2)
	v_cvt_f32_f16_sdwa v97, v94 dst_sel:DWORD dst_unused:UNUSED_PAD src0_sel:WORD_1
	v_cvt_f32_f16_e32 v96, v94
	v_add_co_u32_e32 v94, vcc, s18, v144
	v_cvt_f32_f16_sdwa v89, v100 dst_sel:DWORD dst_unused:UNUSED_PAD src0_sel:WORD_1
	v_cvt_f32_f16_e32 v88, v100
	v_cvt_f32_f16_sdwa v91, v101 dst_sel:DWORD dst_unused:UNUSED_PAD src0_sel:WORD_1
	v_cvt_f32_f16_e32 v90, v101
	v_cvt_f32_f16_sdwa v101, v95 dst_sel:DWORD dst_unused:UNUSED_PAD src0_sel:WORD_1
	v_cvt_f32_f16_e32 v100, v95
	v_addc_co_u32_e32 v95, vcc, 0, v145, vcc
	v_pk_fma_f32 v[102:103], v[80:81], 0.5, v[86:87] op_sel_hi:[1,0,1]
	v_pk_fma_f32 v[104:105], v[78:79], 0.5, v[84:85] op_sel_hi:[1,0,1]
	global_load_dwordx2 v[86:87], v[94:95], off
	global_load_dwordx2 v[84:85], v[94:95], off offset:32
	global_load_dwordx2 v[80:81], v[94:95], off offset:256
	global_load_dwordx2 v[78:79], v[94:95], off offset:288
	v_cvt_f16_f32_e32 v106, v104
	v_cvt_f16_f32_sdwa v107, v105 dst_sel:WORD_1 dst_unused:UNUSED_PAD src0_sel:DWORD
	v_pk_fma_f32 v[76:77], v[76:77], 0.5, v[90:91] op_sel_hi:[1,0,1]
	v_pk_fma_f32 v[74:75], v[74:75], 0.5, v[88:89] op_sel_hi:[1,0,1]
	v_cvt_f16_f32_e32 v90, v76
	v_cvt_f16_f32_e32 v88, v74
	v_cvt_f16_f32_sdwa v89, v75 dst_sel:WORD_1 dst_unused:UNUSED_PAD src0_sel:DWORD
	v_cvt_f16_f32_sdwa v91, v77 dst_sel:WORD_1 dst_unused:UNUSED_PAD src0_sel:DWORD
	v_or_b32_e32 v82, 48, v140
	s_waitcnt lgkmcnt(0)
	v_mov_b32_e32 v83, v141
	v_cvt_f16_f32_e32 v108, v102
	v_cvt_f16_f32_sdwa v109, v103 dst_sel:WORD_1 dst_unused:UNUSED_PAD src0_sel:DWORD
	v_or_b32_e32 v94, v107, v106
	v_lshlrev_b64 v[106:107], 11, v[82:83]
	v_lshl_add_u64 v[106:107], s[16:17], 0, v[106:107]
	v_mul_f32_e32 v75, v75, v75
	v_lshl_add_u64 v[106:107], v[138:139], 1, v[106:107]
	v_or_b32_e32 v88, v89, v88
	v_or_b32_e32 v89, v91, v90
	v_fmac_f32_e32 v75, v74, v74
	v_mul_f32_e32 v74, v77, v77
	v_pk_fma_f32 v[72:73], v[72:73], 0.5, v[98:99] op_sel_hi:[1,0,1]
	v_pk_fma_f32 v[70:71], v[70:71], 0.5, v[92:93] op_sel_hi:[1,0,1]
	v_or_b32_e32 v95, v109, v108
	v_mov_b32_e32 v242, v88
	v_mov_b32_e32 v243, v89
	v_fmac_f32_e32 v74, v76, v76
	v_cvt_f16_f32_e32 v76, v70
	v_cvt_f16_f32_sdwa v77, v71 dst_sel:WORD_1 dst_unused:UNUSED_PAD src0_sel:DWORD
	v_cvt_f16_f32_e32 v88, v72
	v_cvt_f16_f32_sdwa v89, v73 dst_sel:WORD_1 dst_unused:UNUSED_PAD src0_sel:DWORD
	v_mov_b32_e32 v240, v94
	v_mov_b32_e32 v241, v95
	v_mbcnt_lo_u32_b32 v222, -1, 0
	v_mbcnt_hi_u32_b32 v222, -1, v222
	v_bfe_u32 v222, v222, 4, 1
	v_mul_u32_u24_e32 v222, 24, v222
	v_mov_b32_e32 v223, 0
	v_permlane16_swap_b32_e32 v240, v242
	v_permlane16_swap_b32_e32 v241, v243
	v_lshl_add_u64 v[222:223], v[106:107], 0, v[222:223]
	global_store_dwordx4 v[222:223], v[240:243], off sc1
	v_mul_f32_e32 v94, v105, v105
	v_mul_f32_e32 v95, v103, v103
	v_fmac_f32_e32 v94, v104, v104
	v_fmac_f32_e32 v95, v102, v102
	v_add_f32_e32 v94, v94, v95
	v_add_f32_e32 v74, v75, v74
	v_mul_f32_e32 v71, v71, v71
	v_add_f32_e32 v90, v94, v74
	v_or_b32_e32 v74, v77, v76
	v_or_b32_e32 v75, v89, v88
	v_fmac_f32_e32 v71, v70, v70
	v_mul_f32_e32 v70, v73, v73
	v_pk_fma_f32 v[68:69], v[68:69], 0.5, v[100:101] op_sel_hi:[1,0,1]
	v_pk_fma_f32 v[66:67], v[66:67], 0.5, v[96:97] op_sel_hi:[1,0,1]
	v_mov_b32_e32 v244, v74
	v_mov_b32_e32 v245, v75
	v_fmac_f32_e32 v70, v72, v72
	v_cvt_f16_f32_e32 v72, v66
	v_cvt_f16_f32_sdwa v73, v67 dst_sel:WORD_1 dst_unused:UNUSED_PAD src0_sel:DWORD
	v_cvt_f16_f32_e32 v74, v68
	v_cvt_f16_f32_sdwa v75, v69 dst_sel:WORD_1 dst_unused:UNUSED_PAD src0_sel:DWORD
	v_mul_f32_e32 v67, v67, v67
	v_fmac_f32_e32 v67, v66, v66
	v_mul_f32_e32 v66, v69, v69
	v_add_f32_e32 v70, v71, v70
	v_fmac_f32_e32 v66, v68, v68
	v_add_f32_e32 v76, v90, v70
	v_or_b32_e32 v70, v73, v72
	v_or_b32_e32 v71, v75, v74
	v_add_f32_e32 v66, v67, v66
	v_mov_b32_e32 v246, v70
	v_mov_b32_e32 v247, v71
	v_mbcnt_lo_u32_b32 v222, -1, 0
	v_mbcnt_hi_u32_b32 v222, -1, v222
	v_bfe_u32 v222, v222, 4, 1
	v_mul_u32_u24_e32 v222, 24, v222
	v_mov_b32_e32 v223, 0
	v_permlane16_swap_b32_e32 v244, v246
	v_permlane16_swap_b32_e32 v245, v247
	v_lshl_add_u64 v[222:223], v[106:107], 0, v[222:223]
	global_store_dwordx4 v[222:223], v[244:247], off offset:256 sc1
	v_add_f32_e32 v66, v76, v66
	v_mov_b32_e32 v67, v66
	s_nop 1
	v_permlane16_swap_b32_e32 v67, v66
	s_waitcnt lgkmcnt(0)
	v_add_f32_e32 v66, v66, v67
	v_mov_b32_e32 v67, v1
	s_nop 0
	v_mbcnt_lo_u32_b32 v67, -1, v67
	v_mbcnt_hi_u32_b32 v67, -1, v67
	v_lshlrev_b32_e32 v67, 2, v67
	v_xor_b32_e32 v67, 0x80, v67
	ds_bpermute_b32 v67, v67, v66
	s_and_saveexec_b64 s[18:19], s[0:1]
	s_cbranch_execz .LBB0_809
	v_lshlrev_b64 v[68:69], 6, v[82:83]
	v_lshl_add_u64 v[68:69], s[14:15], 0, v[68:69]
	s_waitcnt lgkmcnt(0)
	v_add_f32_e32 v66, v66, v67
	global_store_dword v[68:69], v66, off
.LBB0_809:
	s_or_b64 exec, exec, s[18:19]
	s_waitcnt vmcnt(5)
	v_cvt_f32_f16_sdwa v71, v86 dst_sel:DWORD dst_unused:UNUSED_PAD src0_sel:WORD_1
	v_cvt_f32_f16_e32 v70, v86
	v_cvt_f32_f16_sdwa v73, v87 dst_sel:DWORD dst_unused:UNUSED_PAD src0_sel:WORD_1
	v_cvt_f32_f16_e32 v72, v87
	v_lshl_add_u64 v[68:69], v[140:141], 0, s[96:97]
	s_waitcnt lgkmcnt(0)
	v_lshlrev_b64 v[66:67], 11, v[68:69]
	v_or_b32_e32 v88, 0x8000, v66
	v_mov_b32_e32 v89, v67
	v_lshl_add_u64 v[88:89], v[142:143], 0, v[88:89]
	v_pk_fma_f32 v[90:91], v[64:65], 0.5, v[72:73] op_sel_hi:[1,0,1]
	v_pk_fma_f32 v[92:93], v[62:63], 0.5, v[70:71] op_sel_hi:[1,0,1]
	global_load_dwordx2 v[72:73], v[88:89], off
	global_load_dwordx2 v[70:71], v[88:89], off offset:32
	global_load_dwordx2 v[64:65], v[88:89], off offset:256
	global_load_dwordx2 v[62:63], v[88:89], off offset:288
	s_waitcnt vmcnt(8)
	v_cvt_f32_f16_sdwa v75, v84 dst_sel:DWORD dst_unused:UNUSED_PAD src0_sel:WORD_1
	v_cvt_f32_f16_e32 v74, v84
	v_cvt_f32_f16_sdwa v77, v85 dst_sel:DWORD dst_unused:UNUSED_PAD src0_sel:WORD_1
	v_cvt_f32_f16_e32 v76, v85
	s_waitcnt vmcnt(7)
	v_cvt_f32_f16_sdwa v83, v80 dst_sel:DWORD dst_unused:UNUSED_PAD src0_sel:WORD_1
	v_pk_fma_f32 v[58:59], v[58:59], 0.5, v[74:75] op_sel_hi:[1,0,1]
	v_cvt_f32_f16_e32 v82, v80
	v_pk_fma_f32 v[60:61], v[60:61], 0.5, v[76:77] op_sel_hi:[1,0,1]
	v_cvt_f32_f16_sdwa v85, v81 dst_sel:DWORD dst_unused:UNUSED_PAD src0_sel:WORD_1
	v_cvt_f32_f16_e32 v84, v81
	v_cvt_f16_f32_e32 v74, v58
	v_cvt_f16_f32_sdwa v75, v59 dst_sel:WORD_1 dst_unused:UNUSED_PAD src0_sel:DWORD
	v_cvt_f16_f32_e32 v76, v60
	v_cvt_f16_f32_sdwa v77, v61 dst_sel:WORD_1 dst_unused:UNUSED_PAD src0_sel:DWORD
	s_waitcnt vmcnt(6)
	v_cvt_f32_f16_sdwa v81, v78 dst_sel:DWORD dst_unused:UNUSED_PAD src0_sel:WORD_1
	v_cvt_f32_f16_e32 v80, v78
	v_cvt_f16_f32_e32 v78, v92
	v_cvt_f16_f32_sdwa v94, v93 dst_sel:WORD_1 dst_unused:UNUSED_PAD src0_sel:DWORD
	v_cvt_f16_f32_e32 v95, v90
	v_cvt_f16_f32_sdwa v96, v91 dst_sel:WORD_1 dst_unused:UNUSED_PAD src0_sel:DWORD
	v_lshl_add_u64 v[88:89], s[16:17], 0, v[66:67]
	v_mul_f32_e32 v59, v59, v59
	v_lshl_add_u64 v[88:89], v[138:139], 1, v[88:89]
	v_or_b32_e32 v74, v75, v74
	v_or_b32_e32 v75, v77, v76
	v_fmac_f32_e32 v59, v58, v58
	v_mul_f32_e32 v58, v61, v61
	v_pk_fma_f32 v[56:57], v[56:57], 0.5, v[84:85] op_sel_hi:[1,0,1]
	v_pk_fma_f32 v[54:55], v[54:55], 0.5, v[82:83] op_sel_hi:[1,0,1]
	v_cvt_f32_f16_sdwa v87, v79 dst_sel:DWORD dst_unused:UNUSED_PAD src0_sel:WORD_1
	v_cvt_f32_f16_e32 v86, v79
	v_or_b32_e32 v78, v94, v78
	v_or_b32_e32 v79, v96, v95
	v_mov_b32_e32 v242, v74
	v_mov_b32_e32 v243, v75
	v_fmac_f32_e32 v58, v60, v60
	v_cvt_f16_f32_e32 v60, v54
	v_cvt_f16_f32_sdwa v61, v55 dst_sel:WORD_1 dst_unused:UNUSED_PAD src0_sel:DWORD
	v_cvt_f16_f32_e32 v74, v56
	v_cvt_f16_f32_sdwa v75, v57 dst_sel:WORD_1 dst_unused:UNUSED_PAD src0_sel:DWORD
	v_mov_b32_e32 v240, v78
	v_mov_b32_e32 v241, v79
	v_mbcnt_lo_u32_b32 v222, -1, 0
	v_mbcnt_hi_u32_b32 v222, -1, v222
	v_bfe_u32 v222, v222, 4, 1
	v_mul_u32_u24_e32 v222, 24, v222
	v_mov_b32_e32 v223, 0
	v_permlane16_swap_b32_e32 v240, v242
	v_permlane16_swap_b32_e32 v241, v243
	v_lshl_add_u64 v[222:223], v[88:89], 0, v[222:223]
	global_store_dwordx4 v[222:223], v[240:243], off sc1
	v_mul_f32_e32 v78, v93, v93
	v_mul_f32_e32 v79, v91, v91
	v_fmac_f32_e32 v78, v92, v92
	v_fmac_f32_e32 v79, v90, v90
	v_add_f32_e32 v78, v78, v79
	v_add_f32_e32 v58, v59, v58
	v_mul_f32_e32 v55, v55, v55
	v_add_f32_e32 v76, v78, v58
	v_or_b32_e32 v58, v61, v60
	v_or_b32_e32 v59, v75, v74
	v_fmac_f32_e32 v55, v54, v54
	v_mul_f32_e32 v54, v57, v57
	v_pk_fma_f32 v[52:53], v[52:53], 0.5, v[86:87] op_sel_hi:[1,0,1]
	v_pk_fma_f32 v[50:51], v[50:51], 0.5, v[80:81] op_sel_hi:[1,0,1]
	v_mov_b32_e32 v244, v58
	v_mov_b32_e32 v245, v59
	v_fmac_f32_e32 v54, v56, v56
	v_cvt_f16_f32_e32 v56, v50
	v_cvt_f16_f32_sdwa v57, v51 dst_sel:WORD_1 dst_unused:UNUSED_PAD src0_sel:DWORD
	v_cvt_f16_f32_e32 v58, v52
	v_cvt_f16_f32_sdwa v59, v53 dst_sel:WORD_1 dst_unused:UNUSED_PAD src0_sel:DWORD
	v_mul_f32_e32 v51, v51, v51
	v_fmac_f32_e32 v51, v50, v50
	v_mul_f32_e32 v50, v53, v53
	v_add_f32_e32 v54, v55, v54
	v_fmac_f32_e32 v50, v52, v52
	v_add_f32_e32 v60, v76, v54
	v_or_b32_e32 v54, v57, v56
	v_or_b32_e32 v55, v59, v58
	v_add_f32_e32 v50, v51, v50
	v_mov_b32_e32 v246, v54
	v_mov_b32_e32 v247, v55
	v_mbcnt_lo_u32_b32 v222, -1, 0
	v_mbcnt_hi_u32_b32 v222, -1, v222
	v_bfe_u32 v222, v222, 4, 1
	v_mul_u32_u24_e32 v222, 24, v222
	v_mov_b32_e32 v223, 0
	v_permlane16_swap_b32_e32 v244, v246
	v_permlane16_swap_b32_e32 v245, v247
	v_lshl_add_u64 v[222:223], v[88:89], 0, v[222:223]
	global_store_dwordx4 v[222:223], v[244:247], off offset:256 sc1
	v_add_f32_e32 v50, v60, v50
	v_mov_b32_e32 v51, v50
	s_nop 1
	v_permlane16_swap_b32_e32 v51, v50
	s_waitcnt lgkmcnt(0)
	v_add_f32_e32 v50, v50, v51
	v_mov_b32_e32 v51, v1
	s_nop 0
	v_mbcnt_lo_u32_b32 v51, -1, v51
	v_mbcnt_hi_u32_b32 v51, -1, v51
	v_lshlrev_b32_e32 v51, 2, v51
	v_xor_b32_e32 v51, 0x80, v51
	ds_bpermute_b32 v51, v51, v50
	s_and_saveexec_b64 s[18:19], s[0:1]
	s_cbranch_execz .LBB0_811
	v_lshlrev_b64 v[52:53], 6, v[68:69]
	v_lshl_add_u64 v[52:53], s[14:15], 0, v[52:53]
	s_waitcnt lgkmcnt(0)
	v_add_f32_e32 v50, v50, v51
	global_store_dword v[52:53], v50, off
.LBB0_811:
	s_or_b64 exec, exec, s[18:19]
	s_waitcnt vmcnt(5)
	v_cvt_f32_f16_sdwa v53, v72 dst_sel:DWORD dst_unused:UNUSED_PAD src0_sel:WORD_1
	v_cvt_f32_f16_e32 v52, v72
	v_cvt_f32_f16_sdwa v55, v73 dst_sel:DWORD dst_unused:UNUSED_PAD src0_sel:WORD_1
	v_cvt_f32_f16_e32 v54, v73
	s_waitcnt vmcnt(4)
	v_cvt_f32_f16_sdwa v57, v70 dst_sel:DWORD dst_unused:UNUSED_PAD src0_sel:WORD_1
	v_cvt_f32_f16_e32 v56, v70
	v_cvt_f32_f16_sdwa v59, v71 dst_sel:DWORD dst_unused:UNUSED_PAD src0_sel:WORD_1
	v_cvt_f32_f16_e32 v58, v71
	s_waitcnt vmcnt(3)
	v_cvt_f32_f16_sdwa v61, v64 dst_sel:DWORD dst_unused:UNUSED_PAD src0_sel:WORD_1
	v_cvt_f32_f16_e32 v60, v64
	v_cvt_f32_f16_sdwa v69, v65 dst_sel:DWORD dst_unused:UNUSED_PAD src0_sel:WORD_1
	v_cvt_f32_f16_e32 v68, v65
	s_waitcnt vmcnt(2)
	v_cvt_f32_f16_sdwa v65, v62 dst_sel:DWORD dst_unused:UNUSED_PAD src0_sel:WORD_1
	v_cvt_f32_f16_e32 v64, v62
	v_cvt_f32_f16_sdwa v71, v63 dst_sel:DWORD dst_unused:UNUSED_PAD src0_sel:WORD_1
	v_cvt_f32_f16_e32 v70, v63
	v_or_b32_e32 v62, 0x10000, v66
	v_mov_b32_e32 v63, v67
	v_lshl_add_u64 v[62:63], v[142:143], 0, v[62:63]
	v_pk_fma_f32 v[72:73], v[48:49], 0.5, v[54:55] op_sel_hi:[1,0,1]
	v_pk_fma_f32 v[74:75], v[46:47], 0.5, v[52:53] op_sel_hi:[1,0,1]
	global_load_dwordx2 v[54:55], v[62:63], off
	global_load_dwordx2 v[52:53], v[62:63], off offset:32
	global_load_dwordx2 v[48:49], v[62:63], off offset:256
	global_load_dwordx2 v[46:47], v[62:63], off offset:288
	v_cvt_f16_f32_e32 v76, v74
	v_cvt_f16_f32_sdwa v77, v75 dst_sel:WORD_1 dst_unused:UNUSED_PAD src0_sel:DWORD
	v_pk_fma_f32 v[44:45], v[44:45], 0.5, v[58:59] op_sel_hi:[1,0,1]
	v_pk_fma_f32 v[42:43], v[42:43], 0.5, v[56:57] op_sel_hi:[1,0,1]
	s_mov_b64 s[18:19], 0x90
	v_cvt_f16_f32_e32 v56, v42
	v_cvt_f16_f32_sdwa v57, v43 dst_sel:WORD_1 dst_unused:UNUSED_PAD src0_sel:DWORD
	v_cvt_f16_f32_e32 v58, v44
	v_cvt_f16_f32_sdwa v59, v45 dst_sel:WORD_1 dst_unused:UNUSED_PAD src0_sel:DWORD
	s_waitcnt lgkmcnt(0)
	v_lshl_add_u64 v[50:51], v[140:141], 0, s[18:19]
	v_cvt_f16_f32_e32 v78, v72
	v_cvt_f16_f32_sdwa v79, v73 dst_sel:WORD_1 dst_unused:UNUSED_PAD src0_sel:DWORD
	v_or_b32_e32 v62, v77, v76
	v_lshlrev_b64 v[76:77], 11, v[50:51]
	v_lshl_add_u64 v[76:77], s[16:17], 0, v[76:77]
	v_mul_f32_e32 v43, v43, v43
	v_lshl_add_u64 v[76:77], v[138:139], 1, v[76:77]
	v_or_b32_e32 v56, v57, v56
	v_or_b32_e32 v57, v59, v58
	v_fmac_f32_e32 v43, v42, v42
	v_mul_f32_e32 v42, v45, v45
	v_pk_fma_f32 v[40:41], v[40:41], 0.5, v[68:69] op_sel_hi:[1,0,1]
	v_pk_fma_f32 v[38:39], v[38:39], 0.5, v[60:61] op_sel_hi:[1,0,1]
	v_or_b32_e32 v63, v79, v78
	v_mov_b32_e32 v242, v56
	v_mov_b32_e32 v243, v57
	v_fmac_f32_e32 v42, v44, v44
	v_cvt_f16_f32_e32 v44, v38
	v_cvt_f16_f32_sdwa v45, v39 dst_sel:WORD_1 dst_unused:UNUSED_PAD src0_sel:DWORD
	v_cvt_f16_f32_e32 v56, v40
	v_cvt_f16_f32_sdwa v57, v41 dst_sel:WORD_1 dst_unused:UNUSED_PAD src0_sel:DWORD
	v_mov_b32_e32 v240, v62
	v_mov_b32_e32 v241, v63
	v_mbcnt_lo_u32_b32 v222, -1, 0
	v_mbcnt_hi_u32_b32 v222, -1, v222
	v_bfe_u32 v222, v222, 4, 1
	v_mul_u32_u24_e32 v222, 24, v222
	v_mov_b32_e32 v223, 0
	v_permlane16_swap_b32_e32 v240, v242
	v_permlane16_swap_b32_e32 v241, v243
	v_lshl_add_u64 v[222:223], v[76:77], 0, v[222:223]
	global_store_dwordx4 v[222:223], v[240:243], off sc1
	v_mul_f32_e32 v62, v75, v75
	v_mul_f32_e32 v63, v73, v73
	v_fmac_f32_e32 v62, v74, v74
	v_fmac_f32_e32 v63, v72, v72
	v_add_f32_e32 v62, v62, v63
	v_add_f32_e32 v42, v43, v42
	v_mul_f32_e32 v39, v39, v39
	v_add_f32_e32 v58, v62, v42
	v_or_b32_e32 v42, v45, v44
	v_or_b32_e32 v43, v57, v56
	v_fmac_f32_e32 v39, v38, v38
	v_mul_f32_e32 v38, v41, v41
	v_pk_fma_f32 v[36:37], v[36:37], 0.5, v[70:71] op_sel_hi:[1,0,1]
	v_pk_fma_f32 v[34:35], v[34:35], 0.5, v[64:65] op_sel_hi:[1,0,1]
	v_mov_b32_e32 v244, v42
	v_mov_b32_e32 v245, v43
	v_fmac_f32_e32 v38, v40, v40
	v_cvt_f16_f32_e32 v40, v34
	v_cvt_f16_f32_sdwa v41, v35 dst_sel:WORD_1 dst_unused:UNUSED_PAD src0_sel:DWORD
	v_cvt_f16_f32_e32 v42, v36
	v_cvt_f16_f32_sdwa v43, v37 dst_sel:WORD_1 dst_unused:UNUSED_PAD src0_sel:DWORD
	v_mul_f32_e32 v35, v35, v35
	v_fmac_f32_e32 v35, v34, v34
	v_mul_f32_e32 v34, v37, v37
	v_add_f32_e32 v38, v39, v38
	v_fmac_f32_e32 v34, v36, v36
	v_add_f32_e32 v44, v58, v38
	v_or_b32_e32 v38, v41, v40
	v_or_b32_e32 v39, v43, v42
	v_add_f32_e32 v34, v35, v34
	v_mov_b32_e32 v246, v38
	v_mov_b32_e32 v247, v39
	v_mbcnt_lo_u32_b32 v222, -1, 0
	v_mbcnt_hi_u32_b32 v222, -1, v222
	v_bfe_u32 v222, v222, 4, 1
	v_mul_u32_u24_e32 v222, 24, v222
	v_mov_b32_e32 v223, 0
	v_permlane16_swap_b32_e32 v244, v246
	v_permlane16_swap_b32_e32 v245, v247
	v_lshl_add_u64 v[222:223], v[76:77], 0, v[222:223]
	global_store_dwordx4 v[222:223], v[244:247], off offset:256 sc1
	v_add_f32_e32 v34, v44, v34
	v_mov_b32_e32 v35, v34
	s_nop 1
	v_permlane16_swap_b32_e32 v35, v34
	s_waitcnt lgkmcnt(0)
	v_add_f32_e32 v34, v34, v35
	v_mov_b32_e32 v35, v1
	s_nop 0
	v_mbcnt_lo_u32_b32 v35, -1, v35
	v_mbcnt_hi_u32_b32 v35, -1, v35
	v_lshlrev_b32_e32 v35, 2, v35
	v_xor_b32_e32 v35, 0x80, v35
	ds_bpermute_b32 v35, v35, v34
	s_and_saveexec_b64 s[18:19], s[0:1]
	s_cbranch_execz .LBB0_813
	v_lshlrev_b64 v[36:37], 6, v[50:51]
	v_lshl_add_u64 v[36:37], s[14:15], 0, v[36:37]
	s_waitcnt lgkmcnt(0)
	v_add_f32_e32 v34, v34, v35
	global_store_dword v[36:37], v34, off
.LBB0_813:
	s_or_b64 exec, exec, s[18:19]
	s_waitcnt vmcnt(5)
	v_cvt_f32_f16_sdwa v37, v54 dst_sel:DWORD dst_unused:UNUSED_PAD src0_sel:WORD_1
	v_cvt_f32_f16_e32 v36, v54
	v_cvt_f32_f16_sdwa v39, v55 dst_sel:DWORD dst_unused:UNUSED_PAD src0_sel:WORD_1
	v_cvt_f32_f16_e32 v38, v55
	v_or_b32_e32 v66, 0x18000, v66
	s_waitcnt vmcnt(4)
	v_cvt_f32_f16_sdwa v41, v52 dst_sel:DWORD dst_unused:UNUSED_PAD src0_sel:WORD_1
	v_cvt_f32_f16_e32 v40, v52
	v_cvt_f32_f16_sdwa v43, v53 dst_sel:DWORD dst_unused:UNUSED_PAD src0_sel:WORD_1
	v_cvt_f32_f16_e32 v42, v53
	s_waitcnt vmcnt(3)
	v_cvt_f32_f16_sdwa v45, v48 dst_sel:DWORD dst_unused:UNUSED_PAD src0_sel:WORD_1
	v_cvt_f32_f16_e32 v44, v48
	v_cvt_f32_f16_sdwa v51, v49 dst_sel:DWORD dst_unused:UNUSED_PAD src0_sel:WORD_1
	v_cvt_f32_f16_e32 v50, v49
	s_waitcnt vmcnt(2)
	v_cvt_f32_f16_sdwa v49, v46 dst_sel:DWORD dst_unused:UNUSED_PAD src0_sel:WORD_1
	v_cvt_f32_f16_e32 v48, v46
	v_cvt_f32_f16_sdwa v53, v47 dst_sel:DWORD dst_unused:UNUSED_PAD src0_sel:WORD_1
	v_cvt_f32_f16_e32 v52, v47
	v_lshl_add_u64 v[46:47], v[142:143], 0, v[66:67]
	v_pk_fma_f32 v[54:55], v[32:33], 0.5, v[38:39] op_sel_hi:[1,0,1]
	v_pk_fma_f32 v[56:57], v[30:31], 0.5, v[36:37] op_sel_hi:[1,0,1]
	global_load_dwordx2 v[38:39], v[46:47], off
	global_load_dwordx2 v[36:37], v[46:47], off offset:32
	global_load_dwordx2 v[32:33], v[46:47], off offset:256
	global_load_dwordx2 v[30:31], v[46:47], off offset:288
	v_cvt_f16_f32_e32 v58, v56
	v_cvt_f16_f32_sdwa v59, v57 dst_sel:WORD_1 dst_unused:UNUSED_PAD src0_sel:DWORD
	v_pk_fma_f32 v[28:29], v[28:29], 0.5, v[42:43] op_sel_hi:[1,0,1]
	v_pk_fma_f32 v[26:27], v[26:27], 0.5, v[40:41] op_sel_hi:[1,0,1]
	s_mov_b64 s[18:19], 0xa0
	v_cvt_f16_f32_e32 v40, v26
	v_cvt_f16_f32_sdwa v41, v27 dst_sel:WORD_1 dst_unused:UNUSED_PAD src0_sel:DWORD
	v_cvt_f16_f32_e32 v42, v28
	v_cvt_f16_f32_sdwa v43, v29 dst_sel:WORD_1 dst_unused:UNUSED_PAD src0_sel:DWORD
	s_waitcnt lgkmcnt(0)
	v_lshl_add_u64 v[34:35], v[140:141], 0, s[18:19]
	v_cvt_f16_f32_e32 v60, v54
	v_cvt_f16_f32_sdwa v61, v55 dst_sel:WORD_1 dst_unused:UNUSED_PAD src0_sel:DWORD
	v_or_b32_e32 v46, v59, v58
	v_lshlrev_b64 v[58:59], 11, v[34:35]
	v_lshl_add_u64 v[58:59], s[16:17], 0, v[58:59]
	v_mul_f32_e32 v27, v27, v27
	v_lshl_add_u64 v[58:59], v[138:139], 1, v[58:59]
	v_or_b32_e32 v40, v41, v40
	v_or_b32_e32 v41, v43, v42
	v_fmac_f32_e32 v27, v26, v26
	v_mul_f32_e32 v26, v29, v29
	v_pk_fma_f32 v[24:25], v[24:25], 0.5, v[50:51] op_sel_hi:[1,0,1]
	v_pk_fma_f32 v[22:23], v[22:23], 0.5, v[44:45] op_sel_hi:[1,0,1]
	v_or_b32_e32 v47, v61, v60
	v_mov_b32_e32 v242, v40
	v_mov_b32_e32 v243, v41
	v_fmac_f32_e32 v26, v28, v28
	v_cvt_f16_f32_e32 v28, v22
	v_cvt_f16_f32_sdwa v29, v23 dst_sel:WORD_1 dst_unused:UNUSED_PAD src0_sel:DWORD
	v_cvt_f16_f32_e32 v40, v24
	v_cvt_f16_f32_sdwa v41, v25 dst_sel:WORD_1 dst_unused:UNUSED_PAD src0_sel:DWORD
	v_mov_b32_e32 v240, v46
	v_mov_b32_e32 v241, v47
	v_mbcnt_lo_u32_b32 v222, -1, 0
	v_mbcnt_hi_u32_b32 v222, -1, v222
	v_bfe_u32 v222, v222, 4, 1
	v_mul_u32_u24_e32 v222, 24, v222
	v_mov_b32_e32 v223, 0
	v_permlane16_swap_b32_e32 v240, v242
	v_permlane16_swap_b32_e32 v241, v243
	v_lshl_add_u64 v[222:223], v[58:59], 0, v[222:223]
	global_store_dwordx4 v[222:223], v[240:243], off sc1
	v_mul_f32_e32 v46, v57, v57
	v_mul_f32_e32 v47, v55, v55
	v_fmac_f32_e32 v46, v56, v56
	v_fmac_f32_e32 v47, v54, v54
	v_add_f32_e32 v46, v46, v47
	v_add_f32_e32 v26, v27, v26
	v_mul_f32_e32 v23, v23, v23
	v_add_f32_e32 v42, v46, v26
	v_or_b32_e32 v26, v29, v28
	v_or_b32_e32 v27, v41, v40
	v_fmac_f32_e32 v23, v22, v22
	v_mul_f32_e32 v22, v25, v25
	v_pk_fma_f32 v[20:21], v[20:21], 0.5, v[52:53] op_sel_hi:[1,0,1]
	v_pk_fma_f32 v[18:19], v[18:19], 0.5, v[48:49] op_sel_hi:[1,0,1]
	v_mov_b32_e32 v244, v26
	v_mov_b32_e32 v245, v27
	v_fmac_f32_e32 v22, v24, v24
	v_cvt_f16_f32_e32 v24, v18
	v_cvt_f16_f32_sdwa v25, v19 dst_sel:WORD_1 dst_unused:UNUSED_PAD src0_sel:DWORD
	v_cvt_f16_f32_e32 v26, v20
	v_cvt_f16_f32_sdwa v27, v21 dst_sel:WORD_1 dst_unused:UNUSED_PAD src0_sel:DWORD
	v_mul_f32_e32 v19, v19, v19
	v_fmac_f32_e32 v19, v18, v18
	v_mul_f32_e32 v18, v21, v21
	v_add_f32_e32 v22, v23, v22
	v_fmac_f32_e32 v18, v20, v20
	v_add_f32_e32 v28, v42, v22
	v_or_b32_e32 v22, v25, v24
	v_or_b32_e32 v23, v27, v26
	v_add_f32_e32 v18, v19, v18
	v_mov_b32_e32 v246, v22
	v_mov_b32_e32 v247, v23
	v_mbcnt_lo_u32_b32 v222, -1, 0
	v_mbcnt_hi_u32_b32 v222, -1, v222
	v_bfe_u32 v222, v222, 4, 1
	v_mul_u32_u24_e32 v222, 24, v222
	v_mov_b32_e32 v223, 0
	v_permlane16_swap_b32_e32 v244, v246
	v_permlane16_swap_b32_e32 v245, v247
	v_lshl_add_u64 v[222:223], v[58:59], 0, v[222:223]
	global_store_dwordx4 v[222:223], v[244:247], off offset:256 sc1
	v_add_f32_e32 v18, v28, v18
	v_mov_b32_e32 v19, v18
	s_nop 1
	v_permlane16_swap_b32_e32 v19, v18
	s_waitcnt lgkmcnt(0)
	v_add_f32_e32 v18, v18, v19
	v_mov_b32_e32 v19, v1
	s_nop 0
	v_mbcnt_lo_u32_b32 v19, -1, v19
	v_mbcnt_hi_u32_b32 v19, -1, v19
	v_lshlrev_b32_e32 v19, 2, v19
	v_xor_b32_e32 v19, 0x80, v19
	ds_bpermute_b32 v19, v19, v18
	s_and_saveexec_b64 s[18:19], s[0:1]
	s_cbranch_execz .LBB0_815
	v_lshlrev_b64 v[20:21], 6, v[34:35]
	v_lshl_add_u64 v[20:21], s[14:15], 0, v[20:21]
	s_waitcnt lgkmcnt(0)
	v_add_f32_e32 v18, v18, v19
	global_store_dword v[20:21], v18, off
.LBB0_815:
	s_or_b64 exec, exec, s[18:19]
	s_waitcnt vmcnt(5)
	v_cvt_f32_f16_sdwa v21, v38 dst_sel:DWORD dst_unused:UNUSED_PAD src0_sel:WORD_1
	v_cvt_f32_f16_e32 v20, v38
	v_cvt_f32_f16_sdwa v23, v39 dst_sel:DWORD dst_unused:UNUSED_PAD src0_sel:WORD_1
	v_cvt_f32_f16_e32 v22, v39
	s_waitcnt vmcnt(4)
	v_cvt_f32_f16_sdwa v25, v36 dst_sel:DWORD dst_unused:UNUSED_PAD src0_sel:WORD_1
	v_cvt_f32_f16_e32 v24, v36
	v_pk_fma_f32 v[14:15], v[14:15], 0.5, v[20:21] op_sel_hi:[1,0,1]
	v_cvt_f32_f16_sdwa v27, v37 dst_sel:DWORD dst_unused:UNUSED_PAD src0_sel:WORD_1
	v_cvt_f32_f16_e32 v26, v37
	v_cvt_f16_f32_e32 v20, v14
	v_cvt_f16_f32_sdwa v21, v15 dst_sel:WORD_1 dst_unused:UNUSED_PAD src0_sel:DWORD
	v_pk_fma_f32 v[16:17], v[16:17], 0.5, v[22:23] op_sel_hi:[1,0,1]
	v_mul_f32_e32 v15, v15, v15
	v_fmac_f32_e32 v15, v14, v14
	v_mul_f32_e32 v14, v17, v17
	s_waitcnt vmcnt(3)
	v_cvt_f32_f16_sdwa v29, v32 dst_sel:DWORD dst_unused:UNUSED_PAD src0_sel:WORD_1
	v_cvt_f32_f16_e32 v28, v32
	v_fmac_f32_e32 v14, v16, v16
	v_pk_fma_f32 v[10:11], v[10:11], 0.5, v[24:25] op_sel_hi:[1,0,1]
	v_cvt_f32_f16_sdwa v35, v33 dst_sel:DWORD dst_unused:UNUSED_PAD src0_sel:WORD_1
	v_cvt_f32_f16_e32 v34, v33
	v_or_b32_e32 v20, v21, v20
	v_cvt_f16_f32_e32 v21, v16
	v_add_f32_e32 v16, v15, v14
	v_pk_fma_f32 v[12:13], v[12:13], 0.5, v[26:27] op_sel_hi:[1,0,1]
	v_cvt_f16_f32_e32 v14, v10
	v_cvt_f16_f32_sdwa v15, v11 dst_sel:WORD_1 dst_unused:UNUSED_PAD src0_sel:DWORD
	v_mul_f32_e32 v11, v11, v11
	v_fmac_f32_e32 v11, v10, v10
	v_mul_f32_e32 v10, v13, v13
	v_fmac_f32_e32 v10, v12, v12
	s_waitcnt vmcnt(2)
	v_cvt_f32_f16_sdwa v33, v30 dst_sel:DWORD dst_unused:UNUSED_PAD src0_sel:WORD_1
	v_cvt_f32_f16_e32 v32, v30
	v_add_f32_e32 v10, v11, v10
	v_pk_fma_f32 v[6:7], v[6:7], 0.5, v[28:29] op_sel_hi:[1,0,1]
	v_or_b32_e32 v14, v15, v14
	v_cvt_f16_f32_e32 v15, v12
	v_add_f32_e32 v12, v16, v10
	v_pk_fma_f32 v[8:9], v[8:9], 0.5, v[34:35] op_sel_hi:[1,0,1]
	v_cvt_f16_f32_e32 v10, v6
	v_cvt_f16_f32_sdwa v11, v7 dst_sel:WORD_1 dst_unused:UNUSED_PAD src0_sel:DWORD
	v_mul_f32_e32 v7, v7, v7
	v_fmac_f32_e32 v7, v6, v6
	v_mul_f32_e32 v6, v9, v9
	v_fmac_f32_e32 v6, v8, v8
	v_cvt_f32_f16_sdwa v37, v31 dst_sel:DWORD dst_unused:UNUSED_PAD src0_sel:WORD_1
	v_cvt_f32_f16_e32 v36, v31
	v_add_f32_e32 v6, v7, v6
	v_pk_fma_f32 v[2:3], v[2:3], 0.5, v[32:33] op_sel_hi:[1,0,1]
	v_or_b32_e32 v10, v11, v10
	v_cvt_f16_f32_e32 v11, v8
	v_add_f32_e32 v8, v12, v6
	v_cvt_f16_f32_e32 v6, v2
	v_cvt_f16_f32_sdwa v7, v3 dst_sel:WORD_1 dst_unused:UNUSED_PAD src0_sel:DWORD
	v_cvt_f16_f32_sdwa v22, v17 dst_sel:WORD_1 dst_unused:UNUSED_PAD src0_sel:DWORD
	v_pk_fma_f32 v[4:5], v[4:5], 0.5, v[36:37] op_sel_hi:[1,0,1]
	s_mov_b64 s[18:19], 0xb0
	v_cvt_f16_f32_sdwa v17, v13 dst_sel:WORD_1 dst_unused:UNUSED_PAD src0_sel:DWORD
	v_cvt_f16_f32_sdwa v13, v9 dst_sel:WORD_1 dst_unused:UNUSED_PAD src0_sel:DWORD
	v_or_b32_e32 v6, v7, v6
	v_cvt_f16_f32_e32 v7, v4
	v_cvt_f16_f32_sdwa v9, v5 dst_sel:WORD_1 dst_unused:UNUSED_PAD src0_sel:DWORD
	s_waitcnt lgkmcnt(0)
	v_lshl_add_u64 v[18:19], v[140:141], 0, s[18:19]
	v_mul_f32_e32 v3, v3, v3
	v_or_b32_e32 v21, v22, v21
	v_lshlrev_b64 v[22:23], 11, v[18:19]
	v_fmac_f32_e32 v3, v2, v2
	v_mul_f32_e32 v2, v5, v5
	v_lshl_add_u64 v[22:23], s[16:17], 0, v[22:23]
	v_fmac_f32_e32 v2, v4, v4
	v_lshl_add_u64 v[22:23], v[138:139], 1, v[22:23]
	v_or_b32_e32 v15, v17, v15
	v_or_b32_e32 v11, v13, v11
	v_or_b32_e32 v7, v9, v7
	v_add_f32_e32 v2, v3, v2
	v_mov_b32_e32 v240, v20
	v_mov_b32_e32 v241, v21
	v_mov_b32_e32 v242, v14
	v_mov_b32_e32 v243, v15
	v_mbcnt_lo_u32_b32 v222, -1, 0
	v_mbcnt_hi_u32_b32 v222, -1, v222
	v_bfe_u32 v222, v222, 4, 1
	v_mul_u32_u24_e32 v222, 24, v222
	v_mov_b32_e32 v223, 0
	v_permlane16_swap_b32_e32 v240, v242
	v_permlane16_swap_b32_e32 v241, v243
	v_lshl_add_u64 v[222:223], v[22:23], 0, v[222:223]
	global_store_dwordx4 v[222:223], v[240:243], off sc1
	v_mov_b32_e32 v244, v10
	v_mov_b32_e32 v245, v11
	v_mov_b32_e32 v246, v6
	v_mov_b32_e32 v247, v7
	v_mbcnt_lo_u32_b32 v222, -1, 0
	v_mbcnt_hi_u32_b32 v222, -1, v222
	v_bfe_u32 v222, v222, 4, 1
	v_mul_u32_u24_e32 v222, 24, v222
	v_mov_b32_e32 v223, 0
	v_permlane16_swap_b32_e32 v244, v246
	v_permlane16_swap_b32_e32 v245, v247
	v_lshl_add_u64 v[222:223], v[22:23], 0, v[222:223]
	global_store_dwordx4 v[222:223], v[244:247], off offset:256 sc1
	v_add_f32_e32 v2, v8, v2
	v_mov_b32_e32 v3, v2
	s_nop 1
	v_permlane16_swap_b32_e32 v3, v2
	s_waitcnt lgkmcnt(0)
	v_add_f32_e32 v2, v2, v3
	v_mov_b32_e32 v3, v1
	s_nop 0
	v_mbcnt_lo_u32_b32 v3, -1, v3
	v_mbcnt_hi_u32_b32 v3, -1, v3
	v_lshlrev_b32_e32 v3, 2, v3
	v_xor_b32_e32 v3, 0x80, v3
	ds_bpermute_b32 v3, v3, v2
	s_and_saveexec_b64 s[16:17], s[0:1]
	s_cbranch_execz .LBB0_817
	v_lshlrev_b64 v[4:5], 6, v[18:19]
	v_lshl_add_u64 v[4:5], s[14:15], 0, v[4:5]
	s_waitcnt lgkmcnt(0)
	v_add_f32_e32 v2, v2, v3
	global_store_dword v[4:5], v2, off

.LBB0_825:
	global_load_dword v16, v1, s[6:7] sc1
	global_load_dword v0, v1, s[8:9] sc1
	s_waitcnt lgkmcnt(0)
	global_load_dword v2, v1, s[10:11] sc1
	global_load_dword v3, v1, s[14:15] sc1
	global_load_dword v4, v1, s[16:17] sc1
	global_load_dword v5, v1, s[18:19] sc1
	global_load_dword v6, v1, s[20:21] sc1
	global_load_dword v7, v1, s[22:23] sc1
	global_load_dword v8, v1, s[24:25] sc1
	global_load_dword v9, v1, s[26:27] sc1
	global_load_dword v10, v1, s[28:29] sc1
	global_load_dword v11, v1, s[30:31] sc1
	global_load_dword v12, v1, s[34:35] sc1
	global_load_dword v13, v1, s[36:37] sc1
	global_load_dword v14, v1, s[38:39] sc1
	global_load_dword v15, v1, s[40:41] sc1
	s_mov_b64 s[42:43], -1
	s_mov_b64 s[44:45], -1
	s_waitcnt vmcnt(9)
	v_add_u32_e32 v17, v0, v16
	s_waitcnt vmcnt(9)
	v_add_u32_e32 v17, v17, v2
	s_waitcnt vmcnt(8)
	v_add_u32_e32 v17, v17, v3
	s_waitcnt vmcnt(7)
	v_add_u32_e32 v17, v17, v4
	s_waitcnt vmcnt(6)
	v_add_u32_e32 v17, v17, v5
	s_waitcnt vmcnt(5)
	v_add_u32_e32 v17, v17, v6
	s_waitcnt vmcnt(4)
	v_add_u32_e32 v17, v17, v7
	s_waitcnt vmcnt(4)
	v_add_u32_e32 v17, v17, v8
	s_waitcnt vmcnt(3)
	v_add_u32_e32 v17, v17, v9
	s_waitcnt vmcnt(3)
	v_add_u32_e32 v17, v17, v10
	s_waitcnt vmcnt(2)
	v_add_u32_e32 v17, v17, v11
	s_waitcnt vmcnt(2)
	v_add_u32_e32 v17, v17, v12
	s_waitcnt vmcnt(1)
	v_add_u32_e32 v17, v17, v13
	s_waitcnt vmcnt(1)
	v_add_u32_e32 v17, v17, v14
	s_waitcnt vmcnt(0)
	v_add_u32_e32 v17, v17, v15
	v_cmp_eq_u32_e32 vcc, s62, v17
	s_cbranch_vccnz .LBB0_824
	s_and_b32 s42, s49, 0xff
	s_cmp_eq_u32 s42, 0
	s_mov_b64 s[42:43], -1
	s_mov_b64 s[46:47], -1
	s_sleep 1
	s_cbranch_scc1 .LBB0_829
	s_and_b64 vcc, exec, s[46:47]
	s_cbranch_vccz .LBB0_824

.LBB0_1990:
	s_ashr_i32 s23, s22, 31
	s_lshl_b64 s[22:23], s[22:23], 8
	v_lshl_or_b32 v138, s20, 8, v155
	v_lshl_add_u64 v[140:141], s[22:23], 0, v[132:133]
	s_mov_b32 s13, s33
	v_ashrrev_i32_e32 v139, 31, v138
	v_lshlrev_b64 v[146:147], 11, v[140:141]
	v_lshl_add_u64 v[142:143], s[26:27], 0, v[146:147]
	v_lshlrev_b64 v[148:149], 1, v[138:139]
	s_mov_b32 s13, s33
	v_lshl_add_u64 v[142:143], v[142:143], 0, v[148:149]
	global_load_dwordx2 v[158:159], v[142:143], off
	global_load_dwordx2 v[160:161], v[142:143], off offset:32
	global_load_dwordx2 v[162:163], v[142:143], off offset:256
	global_load_dwordx2 v[164:165], v[142:143], off offset:288
	v_mov_b32_e32 v142, s13
	ds_read2_b32 v[166:167], v142 offset1:1
	v_lshl_add_u64 v[142:143], s[26:27], 0, v[148:149]
	v_lshl_add_u64 v[144:145], v[142:143], 0, v[146:147]
	v_add_co_u32_e32 v168, vcc, s54, v144
	v_lshl_add_u64 v[146:147], s[24:25], 0, v[146:147]
	s_nop 0
	v_addc_co_u32_e32 v169, vcc, 0, v145, vcc
	v_lshl_add_u64 v[170:171], v[146:147], 0, v[148:149]
	global_load_dwordx2 v[152:153], v[168:169], off
	global_load_dwordx2 v[150:151], v[168:169], off offset:32
	global_load_dwordx2 v[148:149], v[168:169], off offset:256
	global_load_dwordx2 v[146:147], v[168:169], off offset:288
	s_waitcnt lgkmcnt(0)
	v_readfirstlane_b32 s13, v166
	v_readfirstlane_b32 s15, v167
	s_lshl_b32 s20, s20, 2
	s_ashr_i32 s21, s20, 31
	s_lshl_b64 s[20:21], s[20:21], 2
	s_add_u32 s13, s13, s20
	s_addc_u32 s15, s15, s21
	s_add_u32 s13, s13, s48
	s_addc_u32 s15, s15, 0
	s_add_u32 s20, s13, 0x10380000
	s_addc_u32 s21, s15, 0
	s_waitcnt vmcnt(0)
	v_cvt_f32_f16_e32 v166, v158
	v_cvt_f32_f16_sdwa v167, v158 dst_sel:DWORD dst_unused:UNUSED_PAD src0_sel:WORD_1
	v_cvt_f32_f16_e32 v158, v159
	v_cvt_f32_f16_sdwa v159, v159 dst_sel:DWORD dst_unused:UNUSED_PAD src0_sel:WORD_1
	v_cvt_f32_f16_e32 v168, v160
	v_cvt_f32_f16_sdwa v169, v160 dst_sel:DWORD dst_unused:UNUSED_PAD src0_sel:WORD_1
	v_cvt_f32_f16_e32 v160, v161
	v_cvt_f32_f16_sdwa v161, v161 dst_sel:DWORD dst_unused:UNUSED_PAD src0_sel:WORD_1
	v_cvt_f32_f16_e32 v172, v162
	v_cvt_f32_f16_sdwa v173, v162 dst_sel:DWORD dst_unused:UNUSED_PAD src0_sel:WORD_1
	v_cvt_f32_f16_e32 v162, v163
	v_cvt_f32_f16_sdwa v163, v163 dst_sel:DWORD dst_unused:UNUSED_PAD src0_sel:WORD_1
	v_cvt_f32_f16_e32 v174, v164
	v_cvt_f32_f16_sdwa v175, v164 dst_sel:DWORD dst_unused:UNUSED_PAD src0_sel:WORD_1
	v_cvt_f32_f16_e32 v164, v165
	v_cvt_f32_f16_sdwa v165, v165 dst_sel:DWORD dst_unused:UNUSED_PAD src0_sel:WORD_1
	v_pk_add_f32 v[128:129], v[128:129], v[158:159]
	v_pk_add_f32 v[126:127], v[126:127], v[166:167]
	v_pk_add_f32 v[124:125], v[124:125], v[160:161]
	v_pk_add_f32 v[122:123], v[122:123], v[168:169]
	v_pk_add_f32 v[120:121], v[120:121], v[162:163]
	v_pk_add_f32 v[118:119], v[118:119], v[172:173]
	v_cvt_f16_f32_e32 v157, v126
	v_cvt_f16_f32_sdwa v158, v127 dst_sel:WORD_1 dst_unused:UNUSED_PAD src0_sel:DWORD
	v_cvt_f16_f32_e32 v159, v128
	v_cvt_f16_f32_sdwa v160, v129 dst_sel:WORD_1 dst_unused:UNUSED_PAD src0_sel:DWORD
	v_pk_add_f32 v[116:117], v[116:117], v[164:165]
	v_mul_f32_e32 v127, v127, v127
	v_mul_f32_e32 v129, v129, v129
	v_cvt_f16_f32_e32 v161, v122
	v_cvt_f16_f32_sdwa v162, v123 dst_sel:WORD_1 dst_unused:UNUSED_PAD src0_sel:DWORD
	v_cvt_f16_f32_e32 v163, v124
	v_cvt_f16_f32_sdwa v164, v125 dst_sel:WORD_1 dst_unused:UNUSED_PAD src0_sel:DWORD
	v_mul_f32_e32 v123, v123, v123
	v_mul_f32_e32 v125, v125, v125
	v_cvt_f16_f32_e32 v165, v118
	v_cvt_f16_f32_sdwa v166, v119 dst_sel:WORD_1 dst_unused:UNUSED_PAD src0_sel:DWORD
	v_cvt_f16_f32_e32 v167, v120
	v_cvt_f16_f32_sdwa v168, v121 dst_sel:WORD_1 dst_unused:UNUSED_PAD src0_sel:DWORD
	v_mul_f32_e32 v169, v119, v119
	v_fmac_f32_e32 v127, v126, v126
	v_fmac_f32_e32 v129, v128, v128
	v_fmac_f32_e32 v123, v122, v122
	v_fmac_f32_e32 v125, v124, v124
	v_fmac_f32_e32 v169, v118, v118
	v_add_f32_e32 v118, v127, v129
	v_add_f32_e32 v119, v123, v125
	v_pk_add_f32 v[114:115], v[114:115], v[174:175]
	v_mul_f32_e32 v172, v121, v121
	v_add_f32_e32 v124, v118, v119
	v_or_b32_e32 v118, v158, v157
	v_or_b32_e32 v119, v160, v159
	v_cvt_f16_f32_e32 v173, v114
	v_cvt_f16_f32_sdwa v174, v115 dst_sel:WORD_1 dst_unused:UNUSED_PAD src0_sel:DWORD
	v_cvt_f16_f32_e32 v175, v116
	v_fmac_f32_e32 v172, v120, v120
	v_or_b32_e32 v120, v162, v161
	v_or_b32_e32 v121, v164, v163
	v_or_b32_e32 v122, v166, v165
	v_or_b32_e32 v123, v168, v167
	v_mov_b32_e32 v240, v118
	v_mov_b32_e32 v241, v119
	v_mov_b32_e32 v242, v120
	v_mov_b32_e32 v243, v121
	v_mbcnt_lo_u32_b32 v222, -1, 0
	v_mbcnt_hi_u32_b32 v222, -1, v222
	v_bfe_u32 v222, v222, 4, 1
	v_mul_u32_u24_e32 v222, 24, v222
	v_mov_b32_e32 v223, 0
	v_permlane16_swap_b32_e32 v240, v242
	v_permlane16_swap_b32_e32 v241, v243
	v_lshl_add_u64 v[222:223], v[170:171], 0, v[222:223]
	global_store_dwordx4 v[222:223], v[240:243], off sc1
	v_mov_b32_e32 v244, v122
	v_mov_b32_e32 v245, v123
	v_cvt_f16_f32_sdwa v119, v117 dst_sel:WORD_1 dst_unused:UNUSED_PAD src0_sel:DWORD
	v_mul_f32_e32 v115, v115, v115
	v_fmac_f32_e32 v115, v114, v114
	v_mul_f32_e32 v114, v117, v117
	v_add_f32_e32 v118, v169, v172
	v_fmac_f32_e32 v114, v116, v116
	v_add_f32_e32 v120, v124, v118
	v_or_b32_e32 v118, v174, v173
	v_or_b32_e32 v119, v119, v175
	v_add_f32_e32 v114, v115, v114
	v_mov_b32_e32 v246, v118
	v_mov_b32_e32 v247, v119
	v_mbcnt_lo_u32_b32 v222, -1, 0
	v_mbcnt_hi_u32_b32 v222, -1, v222
	v_bfe_u32 v222, v222, 4, 1
	v_mul_u32_u24_e32 v222, 24, v222
	v_mov_b32_e32 v223, 0
	v_permlane16_swap_b32_e32 v244, v246
	v_permlane16_swap_b32_e32 v245, v247
	v_lshl_add_u64 v[222:223], v[170:171], 0, v[222:223]
	global_store_dwordx4 v[222:223], v[244:247], off offset:256 sc1
	v_add_f32_e32 v114, v120, v114
	v_mov_b32_e32 v115, v114
	s_nop 1
	v_permlane16_swap_b32_e32 v115, v114
	s_waitcnt lgkmcnt(0)
	v_add_f32_e32 v114, v114, v115
	v_mov_b32_e32 v115, v1
	s_nop 0
	v_mbcnt_lo_u32_b32 v115, -1, v115
	v_mbcnt_hi_u32_b32 v115, -1, v115
	v_lshlrev_b32_e32 v115, 2, v115
	v_xor_b32_e32 v115, 0x80, v115
	ds_bpermute_b32 v115, v115, v114
	s_and_saveexec_b64 s[22:23], s[0:1]
	s_cbranch_execz .LBB0_1992
	v_lshlrev_b64 v[116:117], 6, v[140:141]
	v_lshl_add_u64 v[116:117], s[20:21], 0, v[116:117]
	s_waitcnt lgkmcnt(0)
	v_add_f32_e32 v114, v114, v115
	global_store_dword v[116:117], v114, off
.LBB0_1992:
	s_or_b64 exec, exec, s[22:23]
	v_cvt_f32_f16_sdwa v117, v152 dst_sel:DWORD dst_unused:UNUSED_PAD src0_sel:WORD_1
	v_cvt_f32_f16_e32 v116, v152
	v_cvt_f32_f16_sdwa v119, v153 dst_sel:DWORD dst_unused:UNUSED_PAD src0_sel:WORD_1
	v_cvt_f32_f16_e32 v118, v153
	s_mov_b32 s13, 0x10000
	v_cvt_f32_f16_sdwa v129, v146 dst_sel:DWORD dst_unused:UNUSED_PAD src0_sel:WORD_1
	v_cvt_f32_f16_e32 v128, v146
	v_add_co_u32_e32 v146, vcc, s13, v144
	v_cvt_f32_f16_sdwa v125, v148 dst_sel:DWORD dst_unused:UNUSED_PAD src0_sel:WORD_1
	v_cvt_f32_f16_e32 v124, v148
	v_cvt_f32_f16_sdwa v127, v149 dst_sel:DWORD dst_unused:UNUSED_PAD src0_sel:WORD_1
	v_cvt_f32_f16_e32 v126, v149
	v_cvt_f32_f16_sdwa v149, v147 dst_sel:DWORD dst_unused:UNUSED_PAD src0_sel:WORD_1
	v_cvt_f32_f16_e32 v148, v147
	v_addc_co_u32_e32 v147, vcc, 0, v145, vcc
	v_cvt_f32_f16_sdwa v121, v150 dst_sel:DWORD dst_unused:UNUSED_PAD src0_sel:WORD_1
	v_cvt_f32_f16_e32 v120, v150
	v_cvt_f32_f16_sdwa v123, v151 dst_sel:DWORD dst_unused:UNUSED_PAD src0_sel:WORD_1
	v_cvt_f32_f16_e32 v122, v151
	v_pk_add_f32 v[150:151], v[112:113], v[118:119]
	v_pk_add_f32 v[152:153], v[110:111], v[116:117]
	global_load_dwordx2 v[118:119], v[146:147], off
	global_load_dwordx2 v[116:117], v[146:147], off offset:32
	global_load_dwordx2 v[112:113], v[146:147], off offset:256
	global_load_dwordx2 v[110:111], v[146:147], off offset:288
	v_cvt_f16_f32_e32 v157, v152
	v_cvt_f16_f32_sdwa v158, v153 dst_sel:WORD_1 dst_unused:UNUSED_PAD src0_sel:DWORD
	v_cvt_f16_f32_e32 v159, v150
	v_cvt_f16_f32_sdwa v160, v151 dst_sel:WORD_1 dst_unused:UNUSED_PAD src0_sel:DWORD
	v_pk_add_f32 v[108:109], v[108:109], v[122:123]
	v_pk_add_f32 v[106:107], v[106:107], v[120:121]
	v_cvt_f16_f32_e32 v122, v108
	v_cvt_f16_f32_e32 v120, v106
	v_cvt_f16_f32_sdwa v121, v107 dst_sel:WORD_1 dst_unused:UNUSED_PAD src0_sel:DWORD
	v_cvt_f16_f32_sdwa v123, v109 dst_sel:WORD_1 dst_unused:UNUSED_PAD src0_sel:DWORD
	v_or_b32_e32 v114, 16, v140
	s_waitcnt lgkmcnt(0)
	v_mov_b32_e32 v115, v141
	v_or_b32_e32 v146, v158, v157
	v_or_b32_e32 v147, v160, v159
	v_lshlrev_b64 v[158:159], 11, v[114:115]
	v_lshl_add_u64 v[158:159], s[24:25], 0, v[158:159]
	v_mul_f32_e32 v107, v107, v107
	v_lshl_add_u64 v[158:159], v[138:139], 1, v[158:159]
	v_or_b32_e32 v120, v121, v120
	v_or_b32_e32 v121, v123, v122
	v_fmac_f32_e32 v107, v106, v106
	v_mul_f32_e32 v106, v109, v109
	v_pk_add_f32 v[104:105], v[104:105], v[126:127]
	v_pk_add_f32 v[102:103], v[102:103], v[124:125]
	v_mov_b32_e32 v242, v120
	v_mov_b32_e32 v243, v121
	v_fmac_f32_e32 v106, v108, v108
	v_cvt_f16_f32_e32 v108, v102
	v_cvt_f16_f32_sdwa v109, v103 dst_sel:WORD_1 dst_unused:UNUSED_PAD src0_sel:DWORD
	v_cvt_f16_f32_e32 v120, v104
	v_cvt_f16_f32_sdwa v121, v105 dst_sel:WORD_1 dst_unused:UNUSED_PAD src0_sel:DWORD
	v_mov_b32_e32 v240, v146
	v_mov_b32_e32 v241, v147
	v_mbcnt_lo_u32_b32 v222, -1, 0
	v_mbcnt_hi_u32_b32 v222, -1, v222
	v_bfe_u32 v222, v222, 4, 1
	v_mul_u32_u24_e32 v222, 24, v222
	v_mov_b32_e32 v223, 0
	v_permlane16_swap_b32_e32 v240, v242
	v_permlane16_swap_b32_e32 v241, v243
	v_lshl_add_u64 v[222:223], v[158:159], 0, v[222:223]
	global_store_dwordx4 v[222:223], v[240:243], off sc1
	v_mul_f32_e32 v146, v153, v153
	v_mul_f32_e32 v147, v151, v151
	v_fmac_f32_e32 v146, v152, v152
	v_fmac_f32_e32 v147, v150, v150
	v_add_f32_e32 v146, v146, v147
	v_add_f32_e32 v106, v107, v106
	v_mul_f32_e32 v103, v103, v103
	v_add_f32_e32 v122, v146, v106
	v_or_b32_e32 v106, v109, v108
	v_or_b32_e32 v107, v121, v120
	v_fmac_f32_e32 v103, v102, v102
	v_mul_f32_e32 v102, v105, v105
	v_pk_add_f32 v[100:101], v[100:101], v[148:149]
	v_pk_add_f32 v[98:99], v[98:99], v[128:129]
	v_mov_b32_e32 v244, v106
	v_mov_b32_e32 v245, v107
	v_fmac_f32_e32 v102, v104, v104
	v_cvt_f16_f32_e32 v104, v98
	v_cvt_f16_f32_sdwa v105, v99 dst_sel:WORD_1 dst_unused:UNUSED_PAD src0_sel:DWORD
	v_cvt_f16_f32_e32 v106, v100
	v_cvt_f16_f32_sdwa v107, v101 dst_sel:WORD_1 dst_unused:UNUSED_PAD src0_sel:DWORD
	v_mul_f32_e32 v99, v99, v99
	v_fmac_f32_e32 v99, v98, v98
	v_mul_f32_e32 v98, v101, v101
	v_add_f32_e32 v102, v103, v102
	v_fmac_f32_e32 v98, v100, v100
	v_add_f32_e32 v108, v122, v102
	v_or_b32_e32 v102, v105, v104
	v_or_b32_e32 v103, v107, v106
	v_add_f32_e32 v98, v99, v98
	v_mov_b32_e32 v246, v102
	v_mov_b32_e32 v247, v103
	v_mbcnt_lo_u32_b32 v222, -1, 0
	v_mbcnt_hi_u32_b32 v222, -1, v222
	v_bfe_u32 v222, v222, 4, 1
	v_mul_u32_u24_e32 v222, 24, v222
	v_mov_b32_e32 v223, 0
	v_permlane16_swap_b32_e32 v244, v246
	v_permlane16_swap_b32_e32 v245, v247
	v_lshl_add_u64 v[222:223], v[158:159], 0, v[222:223]
	global_store_dwordx4 v[222:223], v[244:247], off offset:256 sc1
	v_add_f32_e32 v98, v108, v98
	v_mov_b32_e32 v99, v98
	s_nop 1
	v_permlane16_swap_b32_e32 v99, v98
	s_waitcnt lgkmcnt(0)
	v_add_f32_e32 v98, v98, v99
	v_mov_b32_e32 v99, v1
	s_nop 0
	v_mbcnt_lo_u32_b32 v99, -1, v99
	v_mbcnt_hi_u32_b32 v99, -1, v99
	v_lshlrev_b32_e32 v99, 2, v99
	v_xor_b32_e32 v99, 0x80, v99
	ds_bpermute_b32 v99, v99, v98
	s_and_saveexec_b64 s[22:23], s[0:1]
	s_movk_i32 s53, 0x5ff
	s_cbranch_execz .LBB0_1994
	v_lshlrev_b64 v[100:101], 6, v[114:115]
	v_lshl_add_u64 v[100:101], s[20:21], 0, v[100:101]
	s_waitcnt lgkmcnt(0)
	v_add_f32_e32 v98, v98, v99
	global_store_dword v[100:101], v98, off
.LBB0_1994:
	s_or_b64 exec, exec, s[22:23]
	s_waitcnt vmcnt(5)
	v_cvt_f32_f16_sdwa v101, v118 dst_sel:DWORD dst_unused:UNUSED_PAD src0_sel:WORD_1
	v_cvt_f32_f16_e32 v100, v118
	v_cvt_f32_f16_sdwa v103, v119 dst_sel:DWORD dst_unused:UNUSED_PAD src0_sel:WORD_1
	v_cvt_f32_f16_e32 v102, v119
	s_mov_b32 s13, 0x18000
	s_waitcnt vmcnt(3)
	v_cvt_f32_f16_sdwa v109, v112 dst_sel:DWORD dst_unused:UNUSED_PAD src0_sel:WORD_1
	v_cvt_f32_f16_e32 v108, v112
	v_cvt_f32_f16_sdwa v115, v113 dst_sel:DWORD dst_unused:UNUSED_PAD src0_sel:WORD_1
	v_cvt_f32_f16_e32 v114, v113
	s_waitcnt vmcnt(2)
	v_cvt_f32_f16_sdwa v113, v110 dst_sel:DWORD dst_unused:UNUSED_PAD src0_sel:WORD_1
	v_cvt_f32_f16_e32 v112, v110
	v_add_co_u32_e32 v110, vcc, s13, v144
	v_cvt_f32_f16_sdwa v105, v116 dst_sel:DWORD dst_unused:UNUSED_PAD src0_sel:WORD_1
	v_cvt_f32_f16_e32 v104, v116
	v_cvt_f32_f16_sdwa v107, v117 dst_sel:DWORD dst_unused:UNUSED_PAD src0_sel:WORD_1
	v_cvt_f32_f16_e32 v106, v117
	v_cvt_f32_f16_sdwa v117, v111 dst_sel:DWORD dst_unused:UNUSED_PAD src0_sel:WORD_1
	v_cvt_f32_f16_e32 v116, v111
	v_addc_co_u32_e32 v111, vcc, 0, v145, vcc
	v_pk_add_f32 v[118:119], v[96:97], v[102:103]
	v_pk_add_f32 v[120:121], v[94:95], v[100:101]
	global_load_dwordx2 v[102:103], v[110:111], off
	global_load_dwordx2 v[100:101], v[110:111], off offset:32
	global_load_dwordx2 v[96:97], v[110:111], off offset:256
	global_load_dwordx2 v[94:95], v[110:111], off offset:288
	v_cvt_f16_f32_e32 v122, v120
	v_cvt_f16_f32_sdwa v123, v121 dst_sel:WORD_1 dst_unused:UNUSED_PAD src0_sel:DWORD
	v_pk_add_f32 v[92:93], v[92:93], v[106:107]
	v_pk_add_f32 v[90:91], v[90:91], v[104:105]
	v_cvt_f16_f32_e32 v106, v92
	v_cvt_f16_f32_e32 v104, v90
	v_cvt_f16_f32_sdwa v105, v91 dst_sel:WORD_1 dst_unused:UNUSED_PAD src0_sel:DWORD
	v_cvt_f16_f32_sdwa v107, v93 dst_sel:WORD_1 dst_unused:UNUSED_PAD src0_sel:DWORD
	v_or_b32_e32 v98, 32, v140
	s_waitcnt lgkmcnt(0)
	v_mov_b32_e32 v99, v141
	v_cvt_f16_f32_e32 v124, v118
	v_cvt_f16_f32_sdwa v125, v119 dst_sel:WORD_1 dst_unused:UNUSED_PAD src0_sel:DWORD
	v_or_b32_e32 v110, v123, v122
	v_lshlrev_b64 v[122:123], 11, v[98:99]
	v_lshl_add_u64 v[122:123], s[24:25], 0, v[122:123]
	v_mul_f32_e32 v91, v91, v91
	v_lshl_add_u64 v[122:123], v[138:139], 1, v[122:123]
	v_or_b32_e32 v104, v105, v104
	v_or_b32_e32 v105, v107, v106
	v_fmac_f32_e32 v91, v90, v90
	v_mul_f32_e32 v90, v93, v93
	v_pk_add_f32 v[88:89], v[88:89], v[114:115]
	v_pk_add_f32 v[86:87], v[86:87], v[108:109]
	v_or_b32_e32 v111, v125, v124
	v_mov_b32_e32 v242, v104
	v_mov_b32_e32 v243, v105
	v_fmac_f32_e32 v90, v92, v92
	v_cvt_f16_f32_e32 v92, v86
	v_cvt_f16_f32_sdwa v93, v87 dst_sel:WORD_1 dst_unused:UNUSED_PAD src0_sel:DWORD
	v_cvt_f16_f32_e32 v104, v88
	v_cvt_f16_f32_sdwa v105, v89 dst_sel:WORD_1 dst_unused:UNUSED_PAD src0_sel:DWORD
	v_mov_b32_e32 v240, v110
	v_mov_b32_e32 v241, v111
	v_mbcnt_lo_u32_b32 v222, -1, 0
	v_mbcnt_hi_u32_b32 v222, -1, v222
	v_bfe_u32 v222, v222, 4, 1
	v_mul_u32_u24_e32 v222, 24, v222
	v_mov_b32_e32 v223, 0
	v_permlane16_swap_b32_e32 v240, v242
	v_permlane16_swap_b32_e32 v241, v243
	v_lshl_add_u64 v[222:223], v[122:123], 0, v[222:223]
	global_store_dwordx4 v[222:223], v[240:243], off sc1
	v_mul_f32_e32 v110, v121, v121
	v_mul_f32_e32 v111, v119, v119
	v_fmac_f32_e32 v110, v120, v120
	v_fmac_f32_e32 v111, v118, v118
	v_add_f32_e32 v110, v110, v111
	v_add_f32_e32 v90, v91, v90
	v_mul_f32_e32 v87, v87, v87
	v_add_f32_e32 v106, v110, v90
	v_or_b32_e32 v90, v93, v92
	v_or_b32_e32 v91, v105, v104
	v_fmac_f32_e32 v87, v86, v86
	v_mul_f32_e32 v86, v89, v89
	v_pk_add_f32 v[84:85], v[84:85], v[116:117]
	v_pk_add_f32 v[82:83], v[82:83], v[112:113]
	v_mov_b32_e32 v244, v90
	v_mov_b32_e32 v245, v91
	v_fmac_f32_e32 v86, v88, v88
	v_cvt_f16_f32_e32 v88, v82
	v_cvt_f16_f32_sdwa v89, v83 dst_sel:WORD_1 dst_unused:UNUSED_PAD src0_sel:DWORD
	v_cvt_f16_f32_e32 v90, v84
	v_cvt_f16_f32_sdwa v91, v85 dst_sel:WORD_1 dst_unused:UNUSED_PAD src0_sel:DWORD
	v_mul_f32_e32 v83, v83, v83
	v_fmac_f32_e32 v83, v82, v82
	v_mul_f32_e32 v82, v85, v85
	v_add_f32_e32 v86, v87, v86
	v_fmac_f32_e32 v82, v84, v84
	v_add_f32_e32 v92, v106, v86
	v_or_b32_e32 v86, v89, v88
	v_or_b32_e32 v87, v91, v90
	v_add_f32_e32 v82, v83, v82
	v_mov_b32_e32 v246, v86
	v_mov_b32_e32 v247, v87
	v_mbcnt_lo_u32_b32 v222, -1, 0
	v_mbcnt_hi_u32_b32 v222, -1, v222
	v_bfe_u32 v222, v222, 4, 1
	v_mul_u32_u24_e32 v222, 24, v222
	v_mov_b32_e32 v223, 0
	v_permlane16_swap_b32_e32 v244, v246
	v_permlane16_swap_b32_e32 v245, v247
	v_lshl_add_u64 v[222:223], v[122:123], 0, v[222:223]
	global_store_dwordx4 v[222:223], v[244:247], off offset:256 sc1
	v_add_f32_e32 v82, v92, v82
	v_mov_b32_e32 v83, v82
	s_nop 1
	v_permlane16_swap_b32_e32 v83, v82
	s_waitcnt lgkmcnt(0)
	v_add_f32_e32 v82, v82, v83
	v_mov_b32_e32 v83, v1
	s_nop 0
	v_mbcnt_lo_u32_b32 v83, -1, v83
	v_mbcnt_hi_u32_b32 v83, -1, v83
	v_lshlrev_b32_e32 v83, 2, v83
	v_xor_b32_e32 v83, 0x80, v83
	ds_bpermute_b32 v83, v83, v82
	s_and_saveexec_b64 s[22:23], s[0:1]
	s_cbranch_execz .LBB0_1996
	v_lshlrev_b64 v[84:85], 6, v[98:99]
	v_lshl_add_u64 v[84:85], s[20:21], 0, v[84:85]
	s_waitcnt lgkmcnt(0)
	v_add_f32_e32 v82, v82, v83
	global_store_dword v[84:85], v82, off
.LBB0_1996:
	s_or_b64 exec, exec, s[22:23]
	s_waitcnt vmcnt(5)
	v_cvt_f32_f16_sdwa v85, v102 dst_sel:DWORD dst_unused:UNUSED_PAD src0_sel:WORD_1
	v_cvt_f32_f16_e32 v84, v102
	v_cvt_f32_f16_sdwa v87, v103 dst_sel:DWORD dst_unused:UNUSED_PAD src0_sel:WORD_1
	v_cvt_f32_f16_e32 v86, v103
	s_mov_b32 s13, 0x40000
	s_waitcnt vmcnt(3)
	v_cvt_f32_f16_sdwa v93, v96 dst_sel:DWORD dst_unused:UNUSED_PAD src0_sel:WORD_1
	v_cvt_f32_f16_e32 v92, v96
	v_cvt_f32_f16_sdwa v99, v97 dst_sel:DWORD dst_unused:UNUSED_PAD src0_sel:WORD_1
	v_cvt_f32_f16_e32 v98, v97
	s_waitcnt vmcnt(2)
	v_cvt_f32_f16_sdwa v97, v94 dst_sel:DWORD dst_unused:UNUSED_PAD src0_sel:WORD_1
	v_cvt_f32_f16_e32 v96, v94
	v_add_co_u32_e32 v94, vcc, s13, v144
	v_cvt_f32_f16_sdwa v89, v100 dst_sel:DWORD dst_unused:UNUSED_PAD src0_sel:WORD_1
	v_cvt_f32_f16_e32 v88, v100
	v_cvt_f32_f16_sdwa v91, v101 dst_sel:DWORD dst_unused:UNUSED_PAD src0_sel:WORD_1
	v_cvt_f32_f16_e32 v90, v101
	v_cvt_f32_f16_sdwa v101, v95 dst_sel:DWORD dst_unused:UNUSED_PAD src0_sel:WORD_1
	v_cvt_f32_f16_e32 v100, v95
	v_addc_co_u32_e32 v95, vcc, 0, v145, vcc
	v_pk_add_f32 v[102:103], v[80:81], v[86:87]
	v_pk_add_f32 v[104:105], v[78:79], v[84:85]
	global_load_dwordx2 v[86:87], v[94:95], off
	global_load_dwordx2 v[84:85], v[94:95], off offset:32
	global_load_dwordx2 v[80:81], v[94:95], off offset:256
	global_load_dwordx2 v[78:79], v[94:95], off offset:288
	v_cvt_f16_f32_e32 v106, v104
	v_cvt_f16_f32_sdwa v107, v105 dst_sel:WORD_1 dst_unused:UNUSED_PAD src0_sel:DWORD
	v_pk_add_f32 v[76:77], v[76:77], v[90:91]
	v_pk_add_f32 v[74:75], v[74:75], v[88:89]
	v_cvt_f16_f32_e32 v90, v76
	v_cvt_f16_f32_e32 v88, v74
	v_cvt_f16_f32_sdwa v89, v75 dst_sel:WORD_1 dst_unused:UNUSED_PAD src0_sel:DWORD
	v_cvt_f16_f32_sdwa v91, v77 dst_sel:WORD_1 dst_unused:UNUSED_PAD src0_sel:DWORD
	v_or_b32_e32 v82, 48, v140
	s_waitcnt lgkmcnt(0)
	v_mov_b32_e32 v83, v141
	v_cvt_f16_f32_e32 v108, v102
	v_cvt_f16_f32_sdwa v109, v103 dst_sel:WORD_1 dst_unused:UNUSED_PAD src0_sel:DWORD
	v_or_b32_e32 v94, v107, v106
	v_lshlrev_b64 v[106:107], 11, v[82:83]
	v_lshl_add_u64 v[106:107], s[24:25], 0, v[106:107]
	v_mul_f32_e32 v75, v75, v75
	v_lshl_add_u64 v[106:107], v[138:139], 1, v[106:107]
	v_or_b32_e32 v88, v89, v88
	v_or_b32_e32 v89, v91, v90
	v_fmac_f32_e32 v75, v74, v74
	v_mul_f32_e32 v74, v77, v77
	v_pk_add_f32 v[72:73], v[72:73], v[98:99]
	v_pk_add_f32 v[70:71], v[70:71], v[92:93]
	v_or_b32_e32 v95, v109, v108
	v_mov_b32_e32 v242, v88
	v_mov_b32_e32 v243, v89
	v_fmac_f32_e32 v74, v76, v76
	v_cvt_f16_f32_e32 v76, v70
	v_cvt_f16_f32_sdwa v77, v71 dst_sel:WORD_1 dst_unused:UNUSED_PAD src0_sel:DWORD
	v_cvt_f16_f32_e32 v88, v72
	v_cvt_f16_f32_sdwa v89, v73 dst_sel:WORD_1 dst_unused:UNUSED_PAD src0_sel:DWORD
	v_mov_b32_e32 v240, v94
	v_mov_b32_e32 v241, v95
	v_mbcnt_lo_u32_b32 v222, -1, 0
	v_mbcnt_hi_u32_b32 v222, -1, v222
	v_bfe_u32 v222, v222, 4, 1
	v_mul_u32_u24_e32 v222, 24, v222
	v_mov_b32_e32 v223, 0
	v_permlane16_swap_b32_e32 v240, v242
	v_permlane16_swap_b32_e32 v241, v243
	v_lshl_add_u64 v[222:223], v[106:107], 0, v[222:223]
	global_store_dwordx4 v[222:223], v[240:243], off sc1
	v_mul_f32_e32 v94, v105, v105
	v_mul_f32_e32 v95, v103, v103
	v_fmac_f32_e32 v94, v104, v104
	v_fmac_f32_e32 v95, v102, v102
	v_add_f32_e32 v94, v94, v95
	v_add_f32_e32 v74, v75, v74
	v_mul_f32_e32 v71, v71, v71
	v_add_f32_e32 v90, v94, v74
	v_or_b32_e32 v74, v77, v76
	v_or_b32_e32 v75, v89, v88
	v_fmac_f32_e32 v71, v70, v70
	v_mul_f32_e32 v70, v73, v73
	v_pk_add_f32 v[68:69], v[68:69], v[100:101]
	v_pk_add_f32 v[66:67], v[66:67], v[96:97]
	v_mov_b32_e32 v244, v74
	v_mov_b32_e32 v245, v75
	v_fmac_f32_e32 v70, v72, v72
	v_cvt_f16_f32_e32 v72, v66
	v_cvt_f16_f32_sdwa v73, v67 dst_sel:WORD_1 dst_unused:UNUSED_PAD src0_sel:DWORD
	v_cvt_f16_f32_e32 v74, v68
	v_cvt_f16_f32_sdwa v75, v69 dst_sel:WORD_1 dst_unused:UNUSED_PAD src0_sel:DWORD
	v_mul_f32_e32 v67, v67, v67
	v_fmac_f32_e32 v67, v66, v66
	v_mul_f32_e32 v66, v69, v69
	v_add_f32_e32 v70, v71, v70
	v_fmac_f32_e32 v66, v68, v68
	v_add_f32_e32 v76, v90, v70
	v_or_b32_e32 v70, v73, v72
	v_or_b32_e32 v71, v75, v74
	v_add_f32_e32 v66, v67, v66
	v_mov_b32_e32 v246, v70
	v_mov_b32_e32 v247, v71
	v_mbcnt_lo_u32_b32 v222, -1, 0
	v_mbcnt_hi_u32_b32 v222, -1, v222
	v_bfe_u32 v222, v222, 4, 1
	v_mul_u32_u24_e32 v222, 24, v222
	v_mov_b32_e32 v223, 0
	v_permlane16_swap_b32_e32 v244, v246
	v_permlane16_swap_b32_e32 v245, v247
	v_lshl_add_u64 v[222:223], v[106:107], 0, v[222:223]
	global_store_dwordx4 v[222:223], v[244:247], off offset:256 sc1
	v_add_f32_e32 v66, v76, v66
	v_mov_b32_e32 v67, v66
	s_nop 1
	v_permlane16_swap_b32_e32 v67, v66
	s_waitcnt lgkmcnt(0)
	v_add_f32_e32 v66, v66, v67
	v_mov_b32_e32 v67, v1
	s_nop 0
	v_mbcnt_lo_u32_b32 v67, -1, v67
	v_mbcnt_hi_u32_b32 v67, -1, v67
	v_lshlrev_b32_e32 v67, 2, v67
	v_xor_b32_e32 v67, 0x80, v67
	ds_bpermute_b32 v67, v67, v66
	s_and_saveexec_b64 s[22:23], s[0:1]
	s_cbranch_execz .LBB0_1998
	v_lshlrev_b64 v[68:69], 6, v[82:83]
	v_lshl_add_u64 v[68:69], s[20:21], 0, v[68:69]
	s_waitcnt lgkmcnt(0)
	v_add_f32_e32 v66, v66, v67
	global_store_dword v[68:69], v66, off
.LBB0_1998:
	s_or_b64 exec, exec, s[22:23]
	s_waitcnt vmcnt(5)
	v_cvt_f32_f16_sdwa v71, v86 dst_sel:DWORD dst_unused:UNUSED_PAD src0_sel:WORD_1
	v_cvt_f32_f16_e32 v70, v86
	v_cvt_f32_f16_sdwa v73, v87 dst_sel:DWORD dst_unused:UNUSED_PAD src0_sel:WORD_1
	v_cvt_f32_f16_e32 v72, v87
	v_lshl_add_u64 v[68:69], v[140:141], 0, s[96:97]
	s_waitcnt lgkmcnt(0)
	v_lshlrev_b64 v[66:67], 11, v[68:69]
	v_or_b32_e32 v88, 0x8000, v66
	v_mov_b32_e32 v89, v67
	v_lshl_add_u64 v[88:89], v[142:143], 0, v[88:89]
	v_pk_add_f32 v[90:91], v[64:65], v[72:73]
	v_pk_add_f32 v[92:93], v[62:63], v[70:71]
	global_load_dwordx2 v[72:73], v[88:89], off
	global_load_dwordx2 v[70:71], v[88:89], off offset:32
	global_load_dwordx2 v[64:65], v[88:89], off offset:256
	global_load_dwordx2 v[62:63], v[88:89], off offset:288
	s_waitcnt vmcnt(8)
	v_cvt_f32_f16_sdwa v75, v84 dst_sel:DWORD dst_unused:UNUSED_PAD src0_sel:WORD_1
	v_cvt_f32_f16_e32 v74, v84
	v_cvt_f32_f16_sdwa v77, v85 dst_sel:DWORD dst_unused:UNUSED_PAD src0_sel:WORD_1
	v_cvt_f32_f16_e32 v76, v85
	s_waitcnt vmcnt(7)
	v_cvt_f32_f16_sdwa v83, v80 dst_sel:DWORD dst_unused:UNUSED_PAD src0_sel:WORD_1
	v_pk_add_f32 v[58:59], v[58:59], v[74:75]
	v_cvt_f32_f16_e32 v82, v80
	v_pk_add_f32 v[60:61], v[60:61], v[76:77]
	v_cvt_f32_f16_sdwa v85, v81 dst_sel:DWORD dst_unused:UNUSED_PAD src0_sel:WORD_1
	v_cvt_f32_f16_e32 v84, v81
	v_cvt_f16_f32_e32 v74, v58
	v_cvt_f16_f32_sdwa v75, v59 dst_sel:WORD_1 dst_unused:UNUSED_PAD src0_sel:DWORD
	v_cvt_f16_f32_e32 v76, v60
	v_cvt_f16_f32_sdwa v77, v61 dst_sel:WORD_1 dst_unused:UNUSED_PAD src0_sel:DWORD
	s_waitcnt vmcnt(6)
	v_cvt_f32_f16_sdwa v81, v78 dst_sel:DWORD dst_unused:UNUSED_PAD src0_sel:WORD_1
	v_cvt_f32_f16_e32 v80, v78
	v_cvt_f16_f32_e32 v78, v92
	v_cvt_f16_f32_sdwa v94, v93 dst_sel:WORD_1 dst_unused:UNUSED_PAD src0_sel:DWORD
	v_cvt_f16_f32_e32 v95, v90
	v_cvt_f16_f32_sdwa v96, v91 dst_sel:WORD_1 dst_unused:UNUSED_PAD src0_sel:DWORD
	v_lshl_add_u64 v[88:89], s[24:25], 0, v[66:67]
	v_mul_f32_e32 v59, v59, v59
	v_lshl_add_u64 v[88:89], v[138:139], 1, v[88:89]
	v_or_b32_e32 v74, v75, v74
	v_or_b32_e32 v75, v77, v76
	v_fmac_f32_e32 v59, v58, v58
	v_mul_f32_e32 v58, v61, v61
	v_pk_add_f32 v[56:57], v[56:57], v[84:85]
	v_pk_add_f32 v[54:55], v[54:55], v[82:83]
	v_cvt_f32_f16_sdwa v87, v79 dst_sel:DWORD dst_unused:UNUSED_PAD src0_sel:WORD_1
	v_cvt_f32_f16_e32 v86, v79
	v_or_b32_e32 v78, v94, v78
	v_or_b32_e32 v79, v96, v95
	v_mov_b32_e32 v242, v74
	v_mov_b32_e32 v243, v75
	v_fmac_f32_e32 v58, v60, v60
	v_cvt_f16_f32_e32 v60, v54
	v_cvt_f16_f32_sdwa v61, v55 dst_sel:WORD_1 dst_unused:UNUSED_PAD src0_sel:DWORD
	v_cvt_f16_f32_e32 v74, v56
	v_cvt_f16_f32_sdwa v75, v57 dst_sel:WORD_1 dst_unused:UNUSED_PAD src0_sel:DWORD
	v_mov_b32_e32 v240, v78
	v_mov_b32_e32 v241, v79
	v_mbcnt_lo_u32_b32 v222, -1, 0
	v_mbcnt_hi_u32_b32 v222, -1, v222
	v_bfe_u32 v222, v222, 4, 1
	v_mul_u32_u24_e32 v222, 24, v222
	v_mov_b32_e32 v223, 0
	v_permlane16_swap_b32_e32 v240, v242
	v_permlane16_swap_b32_e32 v241, v243
	v_lshl_add_u64 v[222:223], v[88:89], 0, v[222:223]
	global_store_dwordx4 v[222:223], v[240:243], off sc1
	v_mul_f32_e32 v78, v93, v93
	v_mul_f32_e32 v79, v91, v91
	v_fmac_f32_e32 v78, v92, v92
	v_fmac_f32_e32 v79, v90, v90
	v_add_f32_e32 v78, v78, v79
	v_add_f32_e32 v58, v59, v58
	v_mul_f32_e32 v55, v55, v55
	v_add_f32_e32 v76, v78, v58
	v_or_b32_e32 v58, v61, v60
	v_or_b32_e32 v59, v75, v74
	v_fmac_f32_e32 v55, v54, v54
	v_mul_f32_e32 v54, v57, v57
	v_pk_add_f32 v[52:53], v[52:53], v[86:87]
	v_pk_add_f32 v[50:51], v[50:51], v[80:81]
	v_mov_b32_e32 v244, v58
	v_mov_b32_e32 v245, v59
	v_fmac_f32_e32 v54, v56, v56
	v_cvt_f16_f32_e32 v56, v50
	v_cvt_f16_f32_sdwa v57, v51 dst_sel:WORD_1 dst_unused:UNUSED_PAD src0_sel:DWORD
	v_cvt_f16_f32_e32 v58, v52
	v_cvt_f16_f32_sdwa v59, v53 dst_sel:WORD_1 dst_unused:UNUSED_PAD src0_sel:DWORD
	v_mul_f32_e32 v51, v51, v51
	v_fmac_f32_e32 v51, v50, v50
	v_mul_f32_e32 v50, v53, v53
	v_add_f32_e32 v54, v55, v54
	v_fmac_f32_e32 v50, v52, v52
	v_add_f32_e32 v60, v76, v54
	v_or_b32_e32 v54, v57, v56
	v_or_b32_e32 v55, v59, v58
	v_add_f32_e32 v50, v51, v50
	v_mov_b32_e32 v246, v54
	v_mov_b32_e32 v247, v55
	v_mbcnt_lo_u32_b32 v222, -1, 0
	v_mbcnt_hi_u32_b32 v222, -1, v222
	v_bfe_u32 v222, v222, 4, 1
	v_mul_u32_u24_e32 v222, 24, v222
	v_mov_b32_e32 v223, 0
	v_permlane16_swap_b32_e32 v244, v246
	v_permlane16_swap_b32_e32 v245, v247
	v_lshl_add_u64 v[222:223], v[88:89], 0, v[222:223]
	global_store_dwordx4 v[222:223], v[244:247], off offset:256 sc1
	v_add_f32_e32 v50, v60, v50
	v_mov_b32_e32 v51, v50
	s_nop 1
	v_permlane16_swap_b32_e32 v51, v50
	s_waitcnt lgkmcnt(0)
	v_add_f32_e32 v50, v50, v51
	v_mov_b32_e32 v51, v1
	s_nop 0
	v_mbcnt_lo_u32_b32 v51, -1, v51
	v_mbcnt_hi_u32_b32 v51, -1, v51
	v_lshlrev_b32_e32 v51, 2, v51
	v_xor_b32_e32 v51, 0x80, v51
	ds_bpermute_b32 v51, v51, v50
	s_and_saveexec_b64 s[22:23], s[0:1]
	s_cbranch_execz .LBB0_2000
	v_lshlrev_b64 v[52:53], 6, v[68:69]
	v_lshl_add_u64 v[52:53], s[20:21], 0, v[52:53]
	s_waitcnt lgkmcnt(0)
	v_add_f32_e32 v50, v50, v51
	global_store_dword v[52:53], v50, off
.LBB0_2000:
	s_or_b64 exec, exec, s[22:23]
	s_waitcnt vmcnt(5)
	v_cvt_f32_f16_sdwa v53, v72 dst_sel:DWORD dst_unused:UNUSED_PAD src0_sel:WORD_1
	v_cvt_f32_f16_e32 v52, v72
	v_cvt_f32_f16_sdwa v55, v73 dst_sel:DWORD dst_unused:UNUSED_PAD src0_sel:WORD_1
	v_cvt_f32_f16_e32 v54, v73
	s_waitcnt vmcnt(4)
	v_cvt_f32_f16_sdwa v57, v70 dst_sel:DWORD dst_unused:UNUSED_PAD src0_sel:WORD_1
	v_cvt_f32_f16_e32 v56, v70
	v_cvt_f32_f16_sdwa v59, v71 dst_sel:DWORD dst_unused:UNUSED_PAD src0_sel:WORD_1
	v_cvt_f32_f16_e32 v58, v71
	s_waitcnt vmcnt(3)
	v_cvt_f32_f16_sdwa v61, v64 dst_sel:DWORD dst_unused:UNUSED_PAD src0_sel:WORD_1
	v_cvt_f32_f16_e32 v60, v64
	v_cvt_f32_f16_sdwa v69, v65 dst_sel:DWORD dst_unused:UNUSED_PAD src0_sel:WORD_1
	v_cvt_f32_f16_e32 v68, v65
	s_waitcnt vmcnt(2)
	v_cvt_f32_f16_sdwa v65, v62 dst_sel:DWORD dst_unused:UNUSED_PAD src0_sel:WORD_1
	v_cvt_f32_f16_e32 v64, v62
	v_cvt_f32_f16_sdwa v71, v63 dst_sel:DWORD dst_unused:UNUSED_PAD src0_sel:WORD_1
	v_cvt_f32_f16_e32 v70, v63
	v_or_b32_e32 v62, 0x10000, v66
	v_mov_b32_e32 v63, v67
	v_lshl_add_u64 v[62:63], v[142:143], 0, v[62:63]
	v_pk_add_f32 v[72:73], v[48:49], v[54:55]
	v_pk_add_f32 v[74:75], v[46:47], v[52:53]
	global_load_dwordx2 v[54:55], v[62:63], off
	global_load_dwordx2 v[52:53], v[62:63], off offset:32
	global_load_dwordx2 v[48:49], v[62:63], off offset:256
	global_load_dwordx2 v[46:47], v[62:63], off offset:288
	v_cvt_f16_f32_e32 v76, v74
	v_cvt_f16_f32_sdwa v77, v75 dst_sel:WORD_1 dst_unused:UNUSED_PAD src0_sel:DWORD
	v_pk_add_f32 v[44:45], v[44:45], v[58:59]
	v_pk_add_f32 v[42:43], v[42:43], v[56:57]
	s_mov_b64 s[22:23], 0x90
	v_cvt_f16_f32_e32 v56, v42
	v_cvt_f16_f32_sdwa v57, v43 dst_sel:WORD_1 dst_unused:UNUSED_PAD src0_sel:DWORD
	v_cvt_f16_f32_e32 v58, v44
	v_cvt_f16_f32_sdwa v59, v45 dst_sel:WORD_1 dst_unused:UNUSED_PAD src0_sel:DWORD
	s_waitcnt lgkmcnt(0)
	v_lshl_add_u64 v[50:51], v[140:141], 0, s[22:23]
	v_cvt_f16_f32_e32 v78, v72
	v_cvt_f16_f32_sdwa v79, v73 dst_sel:WORD_1 dst_unused:UNUSED_PAD src0_sel:DWORD
	v_or_b32_e32 v62, v77, v76
	v_lshlrev_b64 v[76:77], 11, v[50:51]
	v_lshl_add_u64 v[76:77], s[24:25], 0, v[76:77]
	v_mul_f32_e32 v43, v43, v43
	v_lshl_add_u64 v[76:77], v[138:139], 1, v[76:77]
	v_or_b32_e32 v56, v57, v56
	v_or_b32_e32 v57, v59, v58
	v_fmac_f32_e32 v43, v42, v42
	v_mul_f32_e32 v42, v45, v45
	v_pk_add_f32 v[40:41], v[40:41], v[68:69]
	v_pk_add_f32 v[38:39], v[38:39], v[60:61]
	v_or_b32_e32 v63, v79, v78
	v_mov_b32_e32 v242, v56
	v_mov_b32_e32 v243, v57
	v_fmac_f32_e32 v42, v44, v44
	v_cvt_f16_f32_e32 v44, v38
	v_cvt_f16_f32_sdwa v45, v39 dst_sel:WORD_1 dst_unused:UNUSED_PAD src0_sel:DWORD
	v_cvt_f16_f32_e32 v56, v40
	v_cvt_f16_f32_sdwa v57, v41 dst_sel:WORD_1 dst_unused:UNUSED_PAD src0_sel:DWORD
	v_mov_b32_e32 v240, v62
	v_mov_b32_e32 v241, v63
	v_mbcnt_lo_u32_b32 v222, -1, 0
	v_mbcnt_hi_u32_b32 v222, -1, v222
	v_bfe_u32 v222, v222, 4, 1
	v_mul_u32_u24_e32 v222, 24, v222
	v_mov_b32_e32 v223, 0
	v_permlane16_swap_b32_e32 v240, v242
	v_permlane16_swap_b32_e32 v241, v243
	v_lshl_add_u64 v[222:223], v[76:77], 0, v[222:223]
	global_store_dwordx4 v[222:223], v[240:243], off sc1
	v_mul_f32_e32 v62, v75, v75
	v_mul_f32_e32 v63, v73, v73
	v_fmac_f32_e32 v62, v74, v74
	v_fmac_f32_e32 v63, v72, v72
	v_add_f32_e32 v62, v62, v63
	v_add_f32_e32 v42, v43, v42
	v_mul_f32_e32 v39, v39, v39
	v_add_f32_e32 v58, v62, v42
	v_or_b32_e32 v42, v45, v44
	v_or_b32_e32 v43, v57, v56
	v_fmac_f32_e32 v39, v38, v38
	v_mul_f32_e32 v38, v41, v41
	v_pk_add_f32 v[36:37], v[36:37], v[70:71]
	v_pk_add_f32 v[34:35], v[34:35], v[64:65]
	v_mov_b32_e32 v244, v42
	v_mov_b32_e32 v245, v43
	v_fmac_f32_e32 v38, v40, v40
	v_cvt_f16_f32_e32 v40, v34
	v_cvt_f16_f32_sdwa v41, v35 dst_sel:WORD_1 dst_unused:UNUSED_PAD src0_sel:DWORD
	v_cvt_f16_f32_e32 v42, v36
	v_cvt_f16_f32_sdwa v43, v37 dst_sel:WORD_1 dst_unused:UNUSED_PAD src0_sel:DWORD
	v_mul_f32_e32 v35, v35, v35
	v_fmac_f32_e32 v35, v34, v34
	v_mul_f32_e32 v34, v37, v37
	v_add_f32_e32 v38, v39, v38
	v_fmac_f32_e32 v34, v36, v36
	v_add_f32_e32 v44, v58, v38
	v_or_b32_e32 v38, v41, v40
	v_or_b32_e32 v39, v43, v42
	v_add_f32_e32 v34, v35, v34
	v_mov_b32_e32 v246, v38
	v_mov_b32_e32 v247, v39
	v_mbcnt_lo_u32_b32 v222, -1, 0
	v_mbcnt_hi_u32_b32 v222, -1, v222
	v_bfe_u32 v222, v222, 4, 1
	v_mul_u32_u24_e32 v222, 24, v222
	v_mov_b32_e32 v223, 0
	v_permlane16_swap_b32_e32 v244, v246
	v_permlane16_swap_b32_e32 v245, v247
	v_lshl_add_u64 v[222:223], v[76:77], 0, v[222:223]
	global_store_dwordx4 v[222:223], v[244:247], off offset:256 sc1
	v_add_f32_e32 v34, v44, v34
	v_mov_b32_e32 v35, v34
	s_nop 1
	v_permlane16_swap_b32_e32 v35, v34
	s_waitcnt lgkmcnt(0)
	v_add_f32_e32 v34, v34, v35
	v_mov_b32_e32 v35, v1
	s_nop 0
	v_mbcnt_lo_u32_b32 v35, -1, v35
	v_mbcnt_hi_u32_b32 v35, -1, v35
	v_lshlrev_b32_e32 v35, 2, v35
	v_xor_b32_e32 v35, 0x80, v35
	ds_bpermute_b32 v35, v35, v34
	s_and_saveexec_b64 s[22:23], s[0:1]
	s_cbranch_execz .LBB0_2002
	v_lshlrev_b64 v[36:37], 6, v[50:51]
	v_lshl_add_u64 v[36:37], s[20:21], 0, v[36:37]
	s_waitcnt lgkmcnt(0)
	v_add_f32_e32 v34, v34, v35
	global_store_dword v[36:37], v34, off
.LBB0_2002:
	s_or_b64 exec, exec, s[22:23]
	s_waitcnt vmcnt(5)
	v_cvt_f32_f16_sdwa v37, v54 dst_sel:DWORD dst_unused:UNUSED_PAD src0_sel:WORD_1
	v_cvt_f32_f16_e32 v36, v54
	v_cvt_f32_f16_sdwa v39, v55 dst_sel:DWORD dst_unused:UNUSED_PAD src0_sel:WORD_1
	v_cvt_f32_f16_e32 v38, v55
	v_or_b32_e32 v66, 0x18000, v66
	s_waitcnt vmcnt(4)
	v_cvt_f32_f16_sdwa v41, v52 dst_sel:DWORD dst_unused:UNUSED_PAD src0_sel:WORD_1
	v_cvt_f32_f16_e32 v40, v52
	v_cvt_f32_f16_sdwa v43, v53 dst_sel:DWORD dst_unused:UNUSED_PAD src0_sel:WORD_1
	v_cvt_f32_f16_e32 v42, v53
	s_waitcnt vmcnt(3)
	v_cvt_f32_f16_sdwa v45, v48 dst_sel:DWORD dst_unused:UNUSED_PAD src0_sel:WORD_1
	v_cvt_f32_f16_e32 v44, v48
	v_cvt_f32_f16_sdwa v51, v49 dst_sel:DWORD dst_unused:UNUSED_PAD src0_sel:WORD_1
	v_cvt_f32_f16_e32 v50, v49
	s_waitcnt vmcnt(2)
	v_cvt_f32_f16_sdwa v49, v46 dst_sel:DWORD dst_unused:UNUSED_PAD src0_sel:WORD_1
	v_cvt_f32_f16_e32 v48, v46
	v_cvt_f32_f16_sdwa v53, v47 dst_sel:DWORD dst_unused:UNUSED_PAD src0_sel:WORD_1
	v_cvt_f32_f16_e32 v52, v47
	v_lshl_add_u64 v[46:47], v[142:143], 0, v[66:67]
	v_pk_add_f32 v[54:55], v[32:33], v[38:39]
	v_pk_add_f32 v[56:57], v[30:31], v[36:37]
	global_load_dwordx2 v[38:39], v[46:47], off
	global_load_dwordx2 v[36:37], v[46:47], off offset:32
	global_load_dwordx2 v[32:33], v[46:47], off offset:256
	global_load_dwordx2 v[30:31], v[46:47], off offset:288
	v_cvt_f16_f32_e32 v58, v56
	v_cvt_f16_f32_sdwa v59, v57 dst_sel:WORD_1 dst_unused:UNUSED_PAD src0_sel:DWORD
	v_pk_add_f32 v[28:29], v[28:29], v[42:43]
	v_pk_add_f32 v[26:27], v[26:27], v[40:41]
	s_mov_b64 s[22:23], 0xa0
	v_cvt_f16_f32_e32 v40, v26
	v_cvt_f16_f32_sdwa v41, v27 dst_sel:WORD_1 dst_unused:UNUSED_PAD src0_sel:DWORD
	v_cvt_f16_f32_e32 v42, v28
	v_cvt_f16_f32_sdwa v43, v29 dst_sel:WORD_1 dst_unused:UNUSED_PAD src0_sel:DWORD
	s_waitcnt lgkmcnt(0)
	v_lshl_add_u64 v[34:35], v[140:141], 0, s[22:23]
	v_cvt_f16_f32_e32 v60, v54
	v_cvt_f16_f32_sdwa v61, v55 dst_sel:WORD_1 dst_unused:UNUSED_PAD src0_sel:DWORD
	v_or_b32_e32 v46, v59, v58
	v_lshlrev_b64 v[58:59], 11, v[34:35]
	v_lshl_add_u64 v[58:59], s[24:25], 0, v[58:59]
	v_mul_f32_e32 v27, v27, v27
	v_lshl_add_u64 v[58:59], v[138:139], 1, v[58:59]
	v_or_b32_e32 v40, v41, v40
	v_or_b32_e32 v41, v43, v42
	v_fmac_f32_e32 v27, v26, v26
	v_mul_f32_e32 v26, v29, v29
	v_pk_add_f32 v[24:25], v[24:25], v[50:51]
	v_pk_add_f32 v[22:23], v[22:23], v[44:45]
	v_or_b32_e32 v47, v61, v60
	v_mov_b32_e32 v242, v40
	v_mov_b32_e32 v243, v41
	v_fmac_f32_e32 v26, v28, v28
	v_cvt_f16_f32_e32 v28, v22
	v_cvt_f16_f32_sdwa v29, v23 dst_sel:WORD_1 dst_unused:UNUSED_PAD src0_sel:DWORD
	v_cvt_f16_f32_e32 v40, v24
	v_cvt_f16_f32_sdwa v41, v25 dst_sel:WORD_1 dst_unused:UNUSED_PAD src0_sel:DWORD
	v_mov_b32_e32 v240, v46
	v_mov_b32_e32 v241, v47
	v_mbcnt_lo_u32_b32 v222, -1, 0
	v_mbcnt_hi_u32_b32 v222, -1, v222
	v_bfe_u32 v222, v222, 4, 1
	v_mul_u32_u24_e32 v222, 24, v222
	v_mov_b32_e32 v223, 0
	v_permlane16_swap_b32_e32 v240, v242
	v_permlane16_swap_b32_e32 v241, v243
	v_lshl_add_u64 v[222:223], v[58:59], 0, v[222:223]
	global_store_dwordx4 v[222:223], v[240:243], off sc1
	v_mul_f32_e32 v46, v57, v57
	v_mul_f32_e32 v47, v55, v55
	v_fmac_f32_e32 v46, v56, v56
	v_fmac_f32_e32 v47, v54, v54
	v_add_f32_e32 v46, v46, v47
	v_add_f32_e32 v26, v27, v26
	v_mul_f32_e32 v23, v23, v23
	v_add_f32_e32 v42, v46, v26
	v_or_b32_e32 v26, v29, v28
	v_or_b32_e32 v27, v41, v40
	v_fmac_f32_e32 v23, v22, v22
	v_mul_f32_e32 v22, v25, v25
	v_pk_add_f32 v[20:21], v[20:21], v[52:53]
	v_pk_add_f32 v[18:19], v[18:19], v[48:49]
	v_mov_b32_e32 v244, v26
	v_mov_b32_e32 v245, v27
	v_fmac_f32_e32 v22, v24, v24
	v_cvt_f16_f32_e32 v24, v18
	v_cvt_f16_f32_sdwa v25, v19 dst_sel:WORD_1 dst_unused:UNUSED_PAD src0_sel:DWORD
	v_cvt_f16_f32_e32 v26, v20
	v_cvt_f16_f32_sdwa v27, v21 dst_sel:WORD_1 dst_unused:UNUSED_PAD src0_sel:DWORD
	v_mul_f32_e32 v19, v19, v19
	v_fmac_f32_e32 v19, v18, v18
	v_mul_f32_e32 v18, v21, v21
	v_add_f32_e32 v22, v23, v22
	v_fmac_f32_e32 v18, v20, v20
	v_add_f32_e32 v28, v42, v22
	v_or_b32_e32 v22, v25, v24
	v_or_b32_e32 v23, v27, v26
	v_add_f32_e32 v18, v19, v18
	v_mov_b32_e32 v246, v22
	v_mov_b32_e32 v247, v23
	v_mbcnt_lo_u32_b32 v222, -1, 0
	v_mbcnt_hi_u32_b32 v222, -1, v222
	v_bfe_u32 v222, v222, 4, 1
	v_mul_u32_u24_e32 v222, 24, v222
	v_mov_b32_e32 v223, 0
	v_permlane16_swap_b32_e32 v244, v246
	v_permlane16_swap_b32_e32 v245, v247
	v_lshl_add_u64 v[222:223], v[58:59], 0, v[222:223]
	global_store_dwordx4 v[222:223], v[244:247], off offset:256 sc1
	v_add_f32_e32 v18, v28, v18
	v_mov_b32_e32 v19, v18
	s_nop 1
	v_permlane16_swap_b32_e32 v19, v18
	s_waitcnt lgkmcnt(0)
	v_add_f32_e32 v18, v18, v19
	v_mov_b32_e32 v19, v1
	s_nop 0
	v_mbcnt_lo_u32_b32 v19, -1, v19
	v_mbcnt_hi_u32_b32 v19, -1, v19
	v_lshlrev_b32_e32 v19, 2, v19
	v_xor_b32_e32 v19, 0x80, v19
	ds_bpermute_b32 v19, v19, v18
	s_and_saveexec_b64 s[22:23], s[0:1]
	s_cbranch_execz .LBB0_2004
	v_lshlrev_b64 v[20:21], 6, v[34:35]
	v_lshl_add_u64 v[20:21], s[20:21], 0, v[20:21]
	s_waitcnt lgkmcnt(0)
	v_add_f32_e32 v18, v18, v19
	global_store_dword v[20:21], v18, off
.LBB0_2004:
	s_or_b64 exec, exec, s[22:23]
	s_waitcnt vmcnt(5)
	v_cvt_f32_f16_sdwa v21, v38 dst_sel:DWORD dst_unused:UNUSED_PAD src0_sel:WORD_1
	v_cvt_f32_f16_e32 v20, v38
	v_cvt_f32_f16_sdwa v23, v39 dst_sel:DWORD dst_unused:UNUSED_PAD src0_sel:WORD_1
	v_cvt_f32_f16_e32 v22, v39
	s_waitcnt vmcnt(4)
	v_cvt_f32_f16_sdwa v25, v36 dst_sel:DWORD dst_unused:UNUSED_PAD src0_sel:WORD_1
	v_cvt_f32_f16_e32 v24, v36
	v_pk_add_f32 v[14:15], v[14:15], v[20:21]
	v_cvt_f32_f16_sdwa v27, v37 dst_sel:DWORD dst_unused:UNUSED_PAD src0_sel:WORD_1
	v_cvt_f32_f16_e32 v26, v37
	v_cvt_f16_f32_e32 v20, v14
	v_cvt_f16_f32_sdwa v21, v15 dst_sel:WORD_1 dst_unused:UNUSED_PAD src0_sel:DWORD
	v_pk_add_f32 v[16:17], v[16:17], v[22:23]
	v_mul_f32_e32 v15, v15, v15
	v_fmac_f32_e32 v15, v14, v14
	v_mul_f32_e32 v14, v17, v17
	s_waitcnt vmcnt(3)
	v_cvt_f32_f16_sdwa v29, v32 dst_sel:DWORD dst_unused:UNUSED_PAD src0_sel:WORD_1
	v_cvt_f32_f16_e32 v28, v32
	v_fmac_f32_e32 v14, v16, v16
	v_pk_add_f32 v[10:11], v[10:11], v[24:25]
	v_cvt_f32_f16_sdwa v35, v33 dst_sel:DWORD dst_unused:UNUSED_PAD src0_sel:WORD_1
	v_cvt_f32_f16_e32 v34, v33
	v_or_b32_e32 v20, v21, v20
	v_cvt_f16_f32_e32 v21, v16
	v_add_f32_e32 v16, v15, v14
	v_pk_add_f32 v[12:13], v[12:13], v[26:27]
	v_cvt_f16_f32_e32 v14, v10
	v_cvt_f16_f32_sdwa v15, v11 dst_sel:WORD_1 dst_unused:UNUSED_PAD src0_sel:DWORD
	v_mul_f32_e32 v11, v11, v11
	v_fmac_f32_e32 v11, v10, v10
	v_mul_f32_e32 v10, v13, v13
	v_fmac_f32_e32 v10, v12, v12
	s_waitcnt vmcnt(2)
	v_cvt_f32_f16_sdwa v33, v30 dst_sel:DWORD dst_unused:UNUSED_PAD src0_sel:WORD_1
	v_cvt_f32_f16_e32 v32, v30
	v_add_f32_e32 v10, v11, v10
	v_pk_add_f32 v[6:7], v[6:7], v[28:29]
	v_or_b32_e32 v14, v15, v14
	v_cvt_f16_f32_e32 v15, v12
	v_add_f32_e32 v12, v16, v10
	v_pk_add_f32 v[8:9], v[8:9], v[34:35]
	v_cvt_f16_f32_e32 v10, v6
	v_cvt_f16_f32_sdwa v11, v7 dst_sel:WORD_1 dst_unused:UNUSED_PAD src0_sel:DWORD
	v_mul_f32_e32 v7, v7, v7
	v_fmac_f32_e32 v7, v6, v6
	v_mul_f32_e32 v6, v9, v9
	v_fmac_f32_e32 v6, v8, v8
	v_cvt_f32_f16_sdwa v37, v31 dst_sel:DWORD dst_unused:UNUSED_PAD src0_sel:WORD_1
	v_cvt_f32_f16_e32 v36, v31
	v_add_f32_e32 v6, v7, v6
	v_pk_add_f32 v[2:3], v[2:3], v[32:33]
	v_or_b32_e32 v10, v11, v10
	v_cvt_f16_f32_e32 v11, v8
	v_add_f32_e32 v8, v12, v6
	v_cvt_f16_f32_e32 v6, v2
	v_cvt_f16_f32_sdwa v7, v3 dst_sel:WORD_1 dst_unused:UNUSED_PAD src0_sel:DWORD
	v_cvt_f16_f32_sdwa v22, v17 dst_sel:WORD_1 dst_unused:UNUSED_PAD src0_sel:DWORD
	v_pk_add_f32 v[4:5], v[4:5], v[36:37]
	s_mov_b64 s[22:23], 0xb0
	v_cvt_f16_f32_sdwa v17, v13 dst_sel:WORD_1 dst_unused:UNUSED_PAD src0_sel:DWORD
	v_cvt_f16_f32_sdwa v13, v9 dst_sel:WORD_1 dst_unused:UNUSED_PAD src0_sel:DWORD
	v_or_b32_e32 v6, v7, v6
	v_cvt_f16_f32_e32 v7, v4
	v_cvt_f16_f32_sdwa v9, v5 dst_sel:WORD_1 dst_unused:UNUSED_PAD src0_sel:DWORD
	s_waitcnt lgkmcnt(0)
	v_lshl_add_u64 v[18:19], v[140:141], 0, s[22:23]
	v_mul_f32_e32 v3, v3, v3
	v_or_b32_e32 v21, v22, v21
	v_lshlrev_b64 v[22:23], 11, v[18:19]
	v_fmac_f32_e32 v3, v2, v2
	v_mul_f32_e32 v2, v5, v5
	v_lshl_add_u64 v[22:23], s[24:25], 0, v[22:23]
	v_fmac_f32_e32 v2, v4, v4
	v_lshl_add_u64 v[22:23], v[138:139], 1, v[22:23]
	v_or_b32_e32 v15, v17, v15
	v_or_b32_e32 v11, v13, v11
	v_or_b32_e32 v7, v9, v7
	v_add_f32_e32 v2, v3, v2
	v_mov_b32_e32 v240, v20
	v_mov_b32_e32 v241, v21
	v_mov_b32_e32 v242, v14
	v_mov_b32_e32 v243, v15
	v_mbcnt_lo_u32_b32 v222, -1, 0
	v_mbcnt_hi_u32_b32 v222, -1, v222
	v_bfe_u32 v222, v222, 4, 1
	v_mul_u32_u24_e32 v222, 24, v222
	v_mov_b32_e32 v223, 0
	v_permlane16_swap_b32_e32 v240, v242
	v_permlane16_swap_b32_e32 v241, v243
	v_lshl_add_u64 v[222:223], v[22:23], 0, v[222:223]
	global_store_dwordx4 v[222:223], v[240:243], off sc1
	v_mov_b32_e32 v244, v10
	v_mov_b32_e32 v245, v11
	v_mov_b32_e32 v246, v6
	v_mov_b32_e32 v247, v7
	v_mbcnt_lo_u32_b32 v222, -1, 0
	v_mbcnt_hi_u32_b32 v222, -1, v222
	v_bfe_u32 v222, v222, 4, 1
	v_mul_u32_u24_e32 v222, 24, v222
	v_mov_b32_e32 v223, 0
	v_permlane16_swap_b32_e32 v244, v246
	v_permlane16_swap_b32_e32 v245, v247
	v_lshl_add_u64 v[222:223], v[22:23], 0, v[222:223]
	global_store_dwordx4 v[222:223], v[244:247], off offset:256 sc1
	v_add_f32_e32 v2, v8, v2
	v_mov_b32_e32 v3, v2
	s_nop 1
	v_permlane16_swap_b32_e32 v3, v2
	s_waitcnt lgkmcnt(0)
	v_add_f32_e32 v2, v2, v3
	v_mov_b32_e32 v3, v1
	s_nop 0
	v_mbcnt_lo_u32_b32 v3, -1, v3
	v_mbcnt_hi_u32_b32 v3, -1, v3
	v_lshlrev_b32_e32 v3, 2, v3
	v_xor_b32_e32 v3, 0x80, v3
	ds_bpermute_b32 v3, v3, v2
	s_and_saveexec_b64 s[22:23], s[0:1]
	s_cbranch_execz .LBB0_2006
	v_lshlrev_b64 v[4:5], 6, v[18:19]
	v_lshl_add_u64 v[4:5], s[20:21], 0, v[4:5]
	s_waitcnt lgkmcnt(0)
	v_add_f32_e32 v2, v2, v3
	global_store_dword v[4:5], v2, off
